# drop pre-barrier lgkmcnt(0) in all 5 GEMM K-loops (LDS-read latency overlaps barrier release)
# baseline (speedup 1.0000x reference)
.LBB0_261:
	s_add_u32 s0, s76, 0xfff80080
	s_addc_u32 s1, s77, -1
	s_and_b64 s[84:85], s[84:85], exec
	s_cselect_b32 vcc_hi, s22, s1
	s_cselect_b32 vcc_lo, s23, s0
	s_cselect_b32 s85, s49, s58
	s_cselect_b32 s84, s57, s51
	s_add_i32 s0, 0, 0x10000
	s_add_i32 s1, 0, 0x14000
	v_add_u32_e32 v158, s0, v176
	v_add_u32_e32 v174, s1, v176
	ds_read_b128 v[146:149], v158
	ds_read_b128 v[150:153], v158 offset:1024
	ds_read_b128 v[154:157], v158 offset:2048
	ds_read_b128 v[158:161], v158 offset:3072
	ds_read_b128 v[162:165], v174
	ds_read_b128 v[166:169], v174 offset:1024
	ds_read_b128 v[170:173], v174 offset:2048
	ds_read_b128 v[178:181], v174 offset:3072
	v_lshl_add_u64 v[174:175], s[76:77], 0, v[138:139]
	s_add_i32 m0, s21, 0xc000
	ds_read_b128 v[182:185], v177
	ds_read_b128 v[186:189], v177 offset:1024
	ds_read_b128 v[190:193], v177 offset:2048
	ds_read_b128 v[204:207], v177 offset:3072
	ds_read_b128 v[208:211], v177 offset:4096
	ds_read_b128 v[212:215], v177 offset:5120
	ds_read_b128 v[216:219], v177 offset:6144
	ds_read_b128 v[220:223], v177 offset:7168
	global_load_lds_dwordx4 v[174:175], off
	v_lshl_add_u64 v[174:175], s[76:77], 0, v[140:141]
	s_add_i32 m0, s21, 0xe000
	s_nop 0
	global_load_lds_dwordx4 v[174:175], off
	s_waitcnt vmcnt(8)
	s_barrier
	s_setprio 1
	s_waitcnt lgkmcnt(0)
	v_mfma_f32_16x16x32_bf16 v[126:129], v[146:149], v[182:185], v[126:129]
	v_mfma_f32_16x16x32_bf16 v[122:125], v[154:157], v[182:185], v[122:125]
	v_mfma_f32_16x16x32_bf16 v[110:113], v[146:149], v[190:193], v[110:113]
	v_mfma_f32_16x16x32_bf16 v[106:109], v[154:157], v[190:193], v[106:109]
	v_mfma_f32_16x16x32_bf16 v[94:97], v[146:149], v[208:211], v[94:97]
	v_mfma_f32_16x16x32_bf16 v[90:93], v[154:157], v[208:211], v[90:93]
	v_mfma_f32_16x16x32_bf16 v[78:81], v[146:149], v[216:219], v[78:81]
	v_mfma_f32_16x16x32_bf16 v[74:77], v[154:157], v[216:219], v[74:77]
	v_mfma_f32_16x16x32_bf16 v[126:129], v[150:153], v[186:189], v[126:129]
	v_mfma_f32_16x16x32_bf16 v[122:125], v[158:161], v[186:189], v[122:125]
	v_mfma_f32_16x16x32_bf16 v[110:113], v[150:153], v[204:207], v[110:113]
	v_mfma_f32_16x16x32_bf16 v[106:109], v[158:161], v[204:207], v[106:109]
	v_mfma_f32_16x16x32_bf16 v[94:97], v[150:153], v[212:215], v[94:97]
	v_mfma_f32_16x16x32_bf16 v[90:93], v[158:161], v[212:215], v[90:93]
	v_mfma_f32_16x16x32_bf16 v[78:81], v[150:153], v[220:223], v[78:81]
	v_mfma_f32_16x16x32_bf16 v[74:77], v[158:161], v[220:223], v[74:77]
	s_setprio 0
	s_setprio 1
	v_mfma_f32_16x16x32_bf16 v[118:121], v[162:165], v[182:185], v[118:121]
	v_mfma_f32_16x16x32_bf16 v[114:117], v[170:173], v[182:185], v[114:117]
	v_mfma_f32_16x16x32_bf16 v[102:105], v[162:165], v[190:193], v[102:105]
	v_mfma_f32_16x16x32_bf16 v[98:101], v[170:173], v[190:193], v[98:101]
	v_mfma_f32_16x16x32_bf16 v[86:89], v[162:165], v[208:211], v[86:89]
	v_mfma_f32_16x16x32_bf16 v[82:85], v[170:173], v[208:211], v[82:85]
	v_mfma_f32_16x16x32_bf16 v[70:73], v[162:165], v[216:219], v[70:73]
	v_mfma_f32_16x16x32_bf16 v[66:69], v[170:173], v[216:219], v[66:69]
	v_mfma_f32_16x16x32_bf16 v[118:121], v[166:169], v[186:189], v[118:121]
	v_mfma_f32_16x16x32_bf16 v[114:117], v[178:181], v[186:189], v[114:117]
	v_mfma_f32_16x16x32_bf16 v[102:105], v[166:169], v[204:207], v[102:105]
	v_mfma_f32_16x16x32_bf16 v[98:101], v[178:181], v[204:207], v[98:101]
	v_mfma_f32_16x16x32_bf16 v[86:89], v[166:169], v[212:215], v[86:89]
	v_mfma_f32_16x16x32_bf16 v[82:85], v[178:181], v[212:215], v[82:85]
	v_mfma_f32_16x16x32_bf16 v[70:73], v[166:169], v[220:223], v[70:73]
	v_mfma_f32_16x16x32_bf16 v[66:69], v[178:181], v[220:223], v[66:69]
	s_setprio 0
	s_barrier
	s_add_i32 s0, s0, s20
	v_lshl_add_u64 v[174:175], s[84:85], 0, v[132:133]
	s_mov_b32 m0, s0
	ds_read_b128 v[182:185], v177 offset:16384
	ds_read_b128 v[186:189], v177 offset:17408
	ds_read_b128 v[190:193], v177 offset:18432
	ds_read_b128 v[204:207], v177 offset:19456
	ds_read_b128 v[208:211], v177 offset:20480
	ds_read_b128 v[212:215], v177 offset:21504
	ds_read_b128 v[216:219], v177 offset:22528
	ds_read_b128 v[220:223], v177 offset:23552
	global_load_lds_dwordx4 v[174:175], off
	s_add_i32 m0, s0, 0x2000
	s_add_u32 s94, s84, 0x80000
	v_lshl_add_u64 v[224:225], s[84:85], 0, v[130:131]
	s_addc_u32 s95, s85, 0
	s_add_i32 s0, s1, s20
	global_load_lds_dwordx4 v[224:225], off
	v_lshl_add_u64 v[226:227], s[94:95], 0, v[132:133]
	s_mov_b32 m0, s0
	v_lshl_add_u64 v[228:229], vcc, 0, v[130:131]
	global_load_lds_dwordx4 v[226:227], off
	v_lshl_add_u64 v[226:227], s[94:95], 0, v[130:131]
	s_add_i32 m0, s0, 0x2000
	s_nop 0
	global_load_lds_dwordx4 v[226:227], off
	v_lshl_add_u64 v[226:227], vcc, 0, v[132:133]
	s_mov_b32 m0, s21
	s_nop 0
	global_load_lds_dwordx4 v[226:227], off
	s_mov_b32 m0, s26
	s_nop 0
	global_load_lds_dwordx4 v[228:229], off
	s_waitcnt vmcnt(8)
	s_barrier
	s_setprio 1
	s_waitcnt lgkmcnt(0)
	v_mfma_f32_16x16x32_bf16 v[62:65], v[146:149], v[182:185], v[62:65]
	v_mfma_f32_16x16x32_bf16 v[58:61], v[154:157], v[182:185], v[58:61]
	v_mfma_f32_16x16x32_bf16 v[46:49], v[146:149], v[190:193], v[46:49]
	v_mfma_f32_16x16x32_bf16 v[42:45], v[154:157], v[190:193], v[42:45]
	v_mfma_f32_16x16x32_bf16 v[30:33], v[146:149], v[208:211], v[30:33]
	v_mfma_f32_16x16x32_bf16 v[26:29], v[154:157], v[208:211], v[26:29]
	v_mfma_f32_16x16x32_bf16 v[14:17], v[146:149], v[216:219], v[14:17]
	v_mfma_f32_16x16x32_bf16 v[10:13], v[154:157], v[216:219], v[10:13]
	v_mfma_f32_16x16x32_bf16 v[62:65], v[150:153], v[186:189], v[62:65]
	v_mfma_f32_16x16x32_bf16 v[58:61], v[158:161], v[186:189], v[58:61]
	v_mfma_f32_16x16x32_bf16 v[46:49], v[150:153], v[204:207], v[46:49]
	v_mfma_f32_16x16x32_bf16 v[42:45], v[158:161], v[204:207], v[42:45]
	v_mfma_f32_16x16x32_bf16 v[30:33], v[150:153], v[212:215], v[30:33]
	v_mfma_f32_16x16x32_bf16 v[26:29], v[158:161], v[212:215], v[26:29]
	v_mfma_f32_16x16x32_bf16 v[14:17], v[150:153], v[220:223], v[14:17]
	v_mfma_f32_16x16x32_bf16 v[10:13], v[158:161], v[220:223], v[10:13]
	s_setprio 0
	s_setprio 1
	v_mfma_f32_16x16x32_bf16 v[54:57], v[162:165], v[182:185], v[54:57]
	v_mfma_f32_16x16x32_bf16 v[50:53], v[170:173], v[182:185], v[50:53]
	v_mfma_f32_16x16x32_bf16 v[38:41], v[162:165], v[190:193], v[38:41]
	v_mfma_f32_16x16x32_bf16 v[34:37], v[170:173], v[190:193], v[34:37]
	v_mfma_f32_16x16x32_bf16 v[22:25], v[162:165], v[208:211], v[22:25]
	v_mfma_f32_16x16x32_bf16 v[18:21], v[170:173], v[208:211], v[18:21]
	v_mfma_f32_16x16x32_bf16 v[6:9], v[162:165], v[216:219], v[6:9]
	v_mfma_f32_16x16x32_bf16 v[2:5], v[170:173], v[216:219], v[2:5]
	v_mfma_f32_16x16x32_bf16 v[54:57], v[166:169], v[186:189], v[54:57]
	v_mfma_f32_16x16x32_bf16 v[50:53], v[178:181], v[186:189], v[50:53]
	v_mfma_f32_16x16x32_bf16 v[38:41], v[166:169], v[204:207], v[38:41]
	v_mfma_f32_16x16x32_bf16 v[34:37], v[178:181], v[204:207], v[34:37]
	v_mfma_f32_16x16x32_bf16 v[22:25], v[166:169], v[212:215], v[22:25]
	v_mfma_f32_16x16x32_bf16 v[18:21], v[178:181], v[212:215], v[18:21]
	v_mfma_f32_16x16x32_bf16 v[6:9], v[166:169], v[220:223], v[6:9]
	v_mfma_f32_16x16x32_bf16 v[2:5], v[178:181], v[220:223], v[2:5]
	s_setprio 0
	s_barrier
	s_add_i32 s0, 0, 0x18000
	s_add_i32 s1, 0, 0x1c000
	v_add_u32_e32 v158, s0, v176
	v_add_u32_e32 v178, s1, v176
	ds_read_b128 v[146:149], v158
	ds_read_b128 v[150:153], v158 offset:1024
	ds_read_b128 v[154:157], v158 offset:2048
	ds_read_b128 v[158:161], v158 offset:3072
	ds_read_b128 v[162:165], v178
	ds_read_b128 v[166:169], v178 offset:1024
	ds_read_b128 v[170:173], v178 offset:2048
	ds_read_b128 v[178:181], v178 offset:3072
	s_add_u32 s94, vcc_lo, 0x80000
	s_addc_u32 s95, vcc_hi, 0
	s_mov_b32 m0, s27
	v_lshl_add_u64 v[230:231], s[94:95], 0, v[132:133]
	ds_read_b128 v[182:185], v177 offset:32768
	ds_read_b128 v[186:189], v177 offset:33792
	ds_read_b128 v[190:193], v177 offset:34816
	ds_read_b128 v[204:207], v177 offset:35840
	ds_read_b128 v[208:211], v177 offset:36864
	ds_read_b128 v[212:215], v177 offset:37888
	ds_read_b128 v[216:219], v177 offset:38912
	ds_read_b128 v[220:223], v177 offset:39936
	global_load_lds_dwordx4 v[230:231], off
	v_lshl_add_u64 v[230:231], s[94:95], 0, v[130:131]
	s_mov_b32 m0, s29
	s_nop 0
	global_load_lds_dwordx4 v[230:231], off
	s_waitcnt vmcnt(8)
	s_barrier
	s_setprio 1
	s_waitcnt lgkmcnt(0)
	v_mfma_f32_16x16x32_bf16 v[126:129], v[146:149], v[182:185], v[126:129]
	v_mfma_f32_16x16x32_bf16 v[122:125], v[154:157], v[182:185], v[122:125]
	v_mfma_f32_16x16x32_bf16 v[110:113], v[146:149], v[190:193], v[110:113]
	v_mfma_f32_16x16x32_bf16 v[106:109], v[154:157], v[190:193], v[106:109]
	v_mfma_f32_16x16x32_bf16 v[94:97], v[146:149], v[208:211], v[94:97]
	v_mfma_f32_16x16x32_bf16 v[90:93], v[154:157], v[208:211], v[90:93]
	v_mfma_f32_16x16x32_bf16 v[78:81], v[146:149], v[216:219], v[78:81]
	v_mfma_f32_16x16x32_bf16 v[74:77], v[154:157], v[216:219], v[74:77]
	v_mfma_f32_16x16x32_bf16 v[126:129], v[150:153], v[186:189], v[126:129]
	v_mfma_f32_16x16x32_bf16 v[122:125], v[158:161], v[186:189], v[122:125]
	v_mfma_f32_16x16x32_bf16 v[110:113], v[150:153], v[204:207], v[110:113]
	v_mfma_f32_16x16x32_bf16 v[106:109], v[158:161], v[204:207], v[106:109]
	v_mfma_f32_16x16x32_bf16 v[94:97], v[150:153], v[212:215], v[94:97]
	v_mfma_f32_16x16x32_bf16 v[90:93], v[158:161], v[212:215], v[90:93]
	v_mfma_f32_16x16x32_bf16 v[78:81], v[150:153], v[220:223], v[78:81]
	v_mfma_f32_16x16x32_bf16 v[74:77], v[158:161], v[220:223], v[74:77]
	s_setprio 0
	s_setprio 1
	v_mfma_f32_16x16x32_bf16 v[118:121], v[162:165], v[182:185], v[118:121]
	v_mfma_f32_16x16x32_bf16 v[114:117], v[170:173], v[182:185], v[114:117]
	v_mfma_f32_16x16x32_bf16 v[102:105], v[162:165], v[190:193], v[102:105]
	v_mfma_f32_16x16x32_bf16 v[98:101], v[170:173], v[190:193], v[98:101]
	v_mfma_f32_16x16x32_bf16 v[86:89], v[162:165], v[208:211], v[86:89]
	v_mfma_f32_16x16x32_bf16 v[82:85], v[170:173], v[208:211], v[82:85]
	v_mfma_f32_16x16x32_bf16 v[70:73], v[162:165], v[216:219], v[70:73]
	v_mfma_f32_16x16x32_bf16 v[66:69], v[170:173], v[216:219], v[66:69]
	v_mfma_f32_16x16x32_bf16 v[118:121], v[166:169], v[186:189], v[118:121]
	v_mfma_f32_16x16x32_bf16 v[114:117], v[178:181], v[186:189], v[114:117]
	v_mfma_f32_16x16x32_bf16 v[102:105], v[166:169], v[204:207], v[102:105]
	v_mfma_f32_16x16x32_bf16 v[98:101], v[178:181], v[204:207], v[98:101]
	v_mfma_f32_16x16x32_bf16 v[86:89], v[166:169], v[212:215], v[86:89]
	v_mfma_f32_16x16x32_bf16 v[82:85], v[178:181], v[212:215], v[82:85]
	v_mfma_f32_16x16x32_bf16 v[70:73], v[166:169], v[220:223], v[70:73]
	v_mfma_f32_16x16x32_bf16 v[66:69], v[178:181], v[220:223], v[66:69]
	s_setprio 0
	s_barrier
	s_add_i32 s0, s0, s20
	v_lshl_add_u64 v[174:175], v[174:175], 0, s[82:83]
	s_mov_b32 m0, s0
	ds_read_b128 v[182:185], v177 offset:49152
	ds_read_b128 v[186:189], v177 offset:50176
	ds_read_b128 v[190:193], v177 offset:51200
	ds_read_b128 v[204:207], v177 offset:52224
	ds_read_b128 v[208:211], v177 offset:53248
	ds_read_b128 v[212:215], v177 offset:54272
	ds_read_b128 v[216:219], v177 offset:55296
	ds_read_b128 v[220:223], v177 offset:56320
	global_load_lds_dwordx4 v[174:175], off
	s_add_i32 m0, s0, 0x2000
	s_add_u32 s84, s84, 0x80080
	v_lshl_add_u64 v[174:175], v[224:225], 0, s[82:83]
	s_addc_u32 s85, s85, 0
	s_add_i32 s0, s1, s20
	global_load_lds_dwordx4 v[174:175], off
	v_lshl_add_u64 v[174:175], s[84:85], 0, v[132:133]
	s_mov_b32 m0, s0
	s_nop 0
	global_load_lds_dwordx4 v[174:175], off
	v_lshl_add_u64 v[174:175], s[84:85], 0, v[130:131]
	s_add_i32 m0, s0, 0x2000
	s_nop 0
	global_load_lds_dwordx4 v[174:175], off
	v_lshl_add_u64 v[174:175], v[226:227], 0, s[82:83]
	s_mov_b32 m0, s40
	s_nop 0
	global_load_lds_dwordx4 v[174:175], off
	v_lshl_add_u64 v[174:175], v[228:229], 0, s[82:83]
	s_mov_b32 m0, s41
	s_nop 0
	global_load_lds_dwordx4 v[174:175], off
	s_waitcnt vmcnt(8)
	s_barrier
	s_setprio 1
	s_waitcnt lgkmcnt(0)
	v_mfma_f32_16x16x32_bf16 v[62:65], v[146:149], v[182:185], v[62:65]
	v_mfma_f32_16x16x32_bf16 v[58:61], v[154:157], v[182:185], v[58:61]
	v_mfma_f32_16x16x32_bf16 v[46:49], v[146:149], v[190:193], v[46:49]
	v_mfma_f32_16x16x32_bf16 v[42:45], v[154:157], v[190:193], v[42:45]
	v_mfma_f32_16x16x32_bf16 v[30:33], v[146:149], v[208:211], v[30:33]
	v_mfma_f32_16x16x32_bf16 v[26:29], v[154:157], v[208:211], v[26:29]
	v_mfma_f32_16x16x32_bf16 v[14:17], v[146:149], v[216:219], v[14:17]
	v_mfma_f32_16x16x32_bf16 v[10:13], v[154:157], v[216:219], v[10:13]
	v_mfma_f32_16x16x32_bf16 v[62:65], v[150:153], v[186:189], v[62:65]
	v_mfma_f32_16x16x32_bf16 v[58:61], v[158:161], v[186:189], v[58:61]
	v_mfma_f32_16x16x32_bf16 v[46:49], v[150:153], v[204:207], v[46:49]
	v_mfma_f32_16x16x32_bf16 v[42:45], v[158:161], v[204:207], v[42:45]
	v_mfma_f32_16x16x32_bf16 v[30:33], v[150:153], v[212:215], v[30:33]
	v_mfma_f32_16x16x32_bf16 v[26:29], v[158:161], v[212:215], v[26:29]
	v_mfma_f32_16x16x32_bf16 v[14:17], v[150:153], v[220:223], v[14:17]
	v_mfma_f32_16x16x32_bf16 v[10:13], v[158:161], v[220:223], v[10:13]
	s_setprio 0
	s_setprio 1
	v_mfma_f32_16x16x32_bf16 v[54:57], v[162:165], v[182:185], v[54:57]
	v_mfma_f32_16x16x32_bf16 v[50:53], v[170:173], v[182:185], v[50:53]
	v_mfma_f32_16x16x32_bf16 v[38:41], v[162:165], v[190:193], v[38:41]
	v_mfma_f32_16x16x32_bf16 v[34:37], v[170:173], v[190:193], v[34:37]
	v_mfma_f32_16x16x32_bf16 v[22:25], v[162:165], v[208:211], v[22:25]
	v_mfma_f32_16x16x32_bf16 v[18:21], v[170:173], v[208:211], v[18:21]
	v_mfma_f32_16x16x32_bf16 v[6:9], v[162:165], v[216:219], v[6:9]
	v_mfma_f32_16x16x32_bf16 v[2:5], v[170:173], v[216:219], v[2:5]
	v_mfma_f32_16x16x32_bf16 v[54:57], v[166:169], v[186:189], v[54:57]
	v_mfma_f32_16x16x32_bf16 v[50:53], v[178:181], v[186:189], v[50:53]
	v_mfma_f32_16x16x32_bf16 v[38:41], v[166:169], v[204:207], v[38:41]
	v_mfma_f32_16x16x32_bf16 v[34:37], v[178:181], v[204:207], v[34:37]
	v_mfma_f32_16x16x32_bf16 v[22:25], v[166:169], v[212:215], v[22:25]
	v_mfma_f32_16x16x32_bf16 v[18:21], v[178:181], v[212:215], v[18:21]
	v_mfma_f32_16x16x32_bf16 v[6:9], v[166:169], v[220:223], v[6:9]
	v_mfma_f32_16x16x32_bf16 v[2:5], v[178:181], v[220:223], v[2:5]
	s_setprio 0
	s_barrier
	s_add_i32 s65, s65, 2
	s_add_u32 s76, s76, 0x100
	s_addc_u32 s77, s77, 0
	s_add_u32 s51, s51, 0x100
	s_addc_u32 s58, s58, 0
	s_cmp_gt_u32 s65, 29
	s_cbranch_scc1 .LBB0_264

.LBB0_285:
	s_add_u32 s0, s76, 0xfff80080
	s_addc_u32 s1, s77, -1
	s_and_b64 s[70:71], s[70:71], exec
	s_cselect_b32 vcc_hi, s21, s1
	s_cselect_b32 vcc_lo, s22, s0
	s_cselect_b32 s71, s23, s41
	s_cselect_b32 s70, s39, s7
	s_add_i32 s0, 0, 0x10000
	s_add_i32 s1, 0, 0x14000
	v_add_u32_e32 v146, s0, v1
	v_add_u32_e32 v174, s1, v1
	ds_read_b128 v[134:137], v146
	ds_read_b128 v[138:141], v146 offset:1024
	ds_read_b128 v[142:145], v146 offset:2048
	ds_read_b128 v[146:149], v146 offset:3072
	ds_read_b128 v[150:153], v174
	ds_read_b128 v[154:157], v174 offset:1024
	ds_read_b128 v[158:161], v174 offset:2048
	ds_read_b128 v[174:177], v174 offset:3072
	v_lshl_add_u64 v[220:221], s[76:77], 0, v[170:171]
	s_add_i32 m0, s67, 0xc000
	ds_read_b128 v[178:181], v222
	ds_read_b128 v[182:185], v222 offset:1024
	ds_read_b128 v[186:189], v222 offset:2048
	ds_read_b128 v[190:193], v222 offset:3072
	ds_read_b128 v[204:207], v222 offset:4096
	ds_read_b128 v[208:211], v222 offset:5120
	ds_read_b128 v[212:215], v222 offset:6144
	ds_read_b128 v[216:219], v222 offset:7168
	global_load_lds_dwordx4 v[220:221], off
	v_lshl_add_u64 v[220:221], s[76:77], 0, v[172:173]
	s_add_i32 m0, s67, 0xe000
	s_nop 0
	global_load_lds_dwordx4 v[220:221], off
	s_waitcnt vmcnt(8)
	s_barrier
	s_setprio 1
	s_waitcnt lgkmcnt(0)
	v_mfma_f32_16x16x32_bf16 v[126:129], v[134:137], v[178:181], v[126:129]
	v_mfma_f32_16x16x32_bf16 v[122:125], v[142:145], v[178:181], v[122:125]
	v_mfma_f32_16x16x32_bf16 v[110:113], v[134:137], v[186:189], v[110:113]
	v_mfma_f32_16x16x32_bf16 v[106:109], v[142:145], v[186:189], v[106:109]
	v_mfma_f32_16x16x32_bf16 v[94:97], v[134:137], v[204:207], v[94:97]
	v_mfma_f32_16x16x32_bf16 v[90:93], v[142:145], v[204:207], v[90:93]
	v_mfma_f32_16x16x32_bf16 v[78:81], v[134:137], v[212:215], v[78:81]
	v_mfma_f32_16x16x32_bf16 v[74:77], v[142:145], v[212:215], v[74:77]
	v_mfma_f32_16x16x32_bf16 v[126:129], v[138:141], v[182:185], v[126:129]
	v_mfma_f32_16x16x32_bf16 v[122:125], v[146:149], v[182:185], v[122:125]
	v_mfma_f32_16x16x32_bf16 v[110:113], v[138:141], v[190:193], v[110:113]
	v_mfma_f32_16x16x32_bf16 v[106:109], v[146:149], v[190:193], v[106:109]
	v_mfma_f32_16x16x32_bf16 v[94:97], v[138:141], v[208:211], v[94:97]
	v_mfma_f32_16x16x32_bf16 v[90:93], v[146:149], v[208:211], v[90:93]
	v_mfma_f32_16x16x32_bf16 v[78:81], v[138:141], v[216:219], v[78:81]
	v_mfma_f32_16x16x32_bf16 v[74:77], v[146:149], v[216:219], v[74:77]
	s_setprio 0
	s_setprio 1
	v_mfma_f32_16x16x32_bf16 v[118:121], v[150:153], v[178:181], v[118:121]
	v_mfma_f32_16x16x32_bf16 v[114:117], v[158:161], v[178:181], v[114:117]
	v_mfma_f32_16x16x32_bf16 v[102:105], v[150:153], v[186:189], v[102:105]
	v_mfma_f32_16x16x32_bf16 v[98:101], v[158:161], v[186:189], v[98:101]
	v_mfma_f32_16x16x32_bf16 v[86:89], v[150:153], v[204:207], v[86:89]
	v_mfma_f32_16x16x32_bf16 v[82:85], v[158:161], v[204:207], v[82:85]
	v_mfma_f32_16x16x32_bf16 v[70:73], v[150:153], v[212:215], v[70:73]
	v_mfma_f32_16x16x32_bf16 v[66:69], v[158:161], v[212:215], v[66:69]
	v_mfma_f32_16x16x32_bf16 v[118:121], v[154:157], v[182:185], v[118:121]
	v_mfma_f32_16x16x32_bf16 v[114:117], v[174:177], v[182:185], v[114:117]
	v_mfma_f32_16x16x32_bf16 v[102:105], v[154:157], v[190:193], v[102:105]
	v_mfma_f32_16x16x32_bf16 v[98:101], v[174:177], v[190:193], v[98:101]
	v_mfma_f32_16x16x32_bf16 v[86:89], v[154:157], v[208:211], v[86:89]
	v_mfma_f32_16x16x32_bf16 v[82:85], v[174:177], v[208:211], v[82:85]
	v_mfma_f32_16x16x32_bf16 v[70:73], v[154:157], v[216:219], v[70:73]
	v_mfma_f32_16x16x32_bf16 v[66:69], v[174:177], v[216:219], v[66:69]
	s_setprio 0
	s_barrier
	s_add_i32 s0, s0, s54
	v_lshl_add_u64 v[220:221], s[70:71], 0, v[164:165]
	s_mov_b32 m0, s0
	ds_read_b128 v[178:181], v222 offset:16384
	ds_read_b128 v[182:185], v222 offset:17408
	ds_read_b128 v[186:189], v222 offset:18432
	ds_read_b128 v[190:193], v222 offset:19456
	ds_read_b128 v[204:207], v222 offset:20480
	ds_read_b128 v[208:211], v222 offset:21504
	ds_read_b128 v[212:215], v222 offset:22528
	ds_read_b128 v[216:219], v222 offset:23552
	global_load_lds_dwordx4 v[220:221], off
	s_add_i32 m0, s0, 0x2000
	s_add_u32 s44, s70, 0x80000
	v_lshl_add_u64 v[224:225], s[70:71], 0, v[162:163]
	s_addc_u32 s45, s71, 0
	s_add_i32 s0, s1, s54
	global_load_lds_dwordx4 v[224:225], off
	v_lshl_add_u64 v[226:227], s[44:45], 0, v[164:165]
	s_mov_b32 m0, s0
	v_lshl_add_u64 v[228:229], vcc, 0, v[162:163]
	global_load_lds_dwordx4 v[226:227], off
	v_lshl_add_u64 v[226:227], s[44:45], 0, v[162:163]
	s_add_i32 m0, s0, 0x2000
	s_nop 0
	global_load_lds_dwordx4 v[226:227], off
	v_lshl_add_u64 v[226:227], vcc, 0, v[164:165]
	s_mov_b32 m0, s67
	s_nop 0
	global_load_lds_dwordx4 v[226:227], off
	s_mov_b32 m0, s68
	s_nop 0
	global_load_lds_dwordx4 v[228:229], off
	s_waitcnt vmcnt(8)
	s_barrier
	s_setprio 1
	s_waitcnt lgkmcnt(0)
	v_mfma_f32_16x16x32_bf16 v[62:65], v[134:137], v[178:181], v[62:65]
	v_mfma_f32_16x16x32_bf16 v[58:61], v[142:145], v[178:181], v[58:61]
	v_mfma_f32_16x16x32_bf16 v[46:49], v[134:137], v[186:189], v[46:49]
	v_mfma_f32_16x16x32_bf16 v[42:45], v[142:145], v[186:189], v[42:45]
	v_mfma_f32_16x16x32_bf16 v[30:33], v[134:137], v[204:207], v[30:33]
	v_mfma_f32_16x16x32_bf16 v[26:29], v[142:145], v[204:207], v[26:29]
	v_mfma_f32_16x16x32_bf16 v[14:17], v[134:137], v[212:215], v[14:17]
	v_mfma_f32_16x16x32_bf16 v[10:13], v[142:145], v[212:215], v[10:13]
	v_mfma_f32_16x16x32_bf16 v[62:65], v[138:141], v[182:185], v[62:65]
	v_mfma_f32_16x16x32_bf16 v[58:61], v[146:149], v[182:185], v[58:61]
	v_mfma_f32_16x16x32_bf16 v[46:49], v[138:141], v[190:193], v[46:49]
	v_mfma_f32_16x16x32_bf16 v[42:45], v[146:149], v[190:193], v[42:45]
	v_mfma_f32_16x16x32_bf16 v[30:33], v[138:141], v[208:211], v[30:33]
	v_mfma_f32_16x16x32_bf16 v[26:29], v[146:149], v[208:211], v[26:29]
	v_mfma_f32_16x16x32_bf16 v[14:17], v[138:141], v[216:219], v[14:17]
	v_mfma_f32_16x16x32_bf16 v[10:13], v[146:149], v[216:219], v[10:13]
	s_setprio 0
	s_setprio 1
	v_mfma_f32_16x16x32_bf16 v[54:57], v[150:153], v[178:181], v[54:57]
	v_mfma_f32_16x16x32_bf16 v[50:53], v[158:161], v[178:181], v[50:53]
	v_mfma_f32_16x16x32_bf16 v[38:41], v[150:153], v[186:189], v[38:41]
	v_mfma_f32_16x16x32_bf16 v[34:37], v[158:161], v[186:189], v[34:37]
	v_mfma_f32_16x16x32_bf16 v[22:25], v[150:153], v[204:207], v[22:25]
	v_mfma_f32_16x16x32_bf16 v[18:21], v[158:161], v[204:207], v[18:21]
	v_mfma_f32_16x16x32_bf16 v[6:9], v[150:153], v[212:215], v[6:9]
	v_mfma_f32_16x16x32_bf16 v[2:5], v[158:161], v[212:215], v[2:5]
	v_mfma_f32_16x16x32_bf16 v[54:57], v[154:157], v[182:185], v[54:57]
	v_mfma_f32_16x16x32_bf16 v[50:53], v[174:177], v[182:185], v[50:53]
	v_mfma_f32_16x16x32_bf16 v[38:41], v[154:157], v[190:193], v[38:41]
	v_mfma_f32_16x16x32_bf16 v[34:37], v[174:177], v[190:193], v[34:37]
	v_mfma_f32_16x16x32_bf16 v[22:25], v[154:157], v[208:211], v[22:25]
	v_mfma_f32_16x16x32_bf16 v[18:21], v[174:177], v[208:211], v[18:21]
	v_mfma_f32_16x16x32_bf16 v[6:9], v[154:157], v[216:219], v[6:9]
	v_mfma_f32_16x16x32_bf16 v[2:5], v[174:177], v[216:219], v[2:5]
	s_setprio 0
	s_barrier
	s_add_i32 s0, 0, 0x18000
	s_add_i32 s1, 0, 0x1c000
	v_add_u32_e32 v146, s0, v1
	v_add_u32_e32 v174, s1, v1
	ds_read_b128 v[134:137], v146
	ds_read_b128 v[138:141], v146 offset:1024
	ds_read_b128 v[142:145], v146 offset:2048
	ds_read_b128 v[146:149], v146 offset:3072
	ds_read_b128 v[150:153], v174
	ds_read_b128 v[154:157], v174 offset:1024
	ds_read_b128 v[158:161], v174 offset:2048
	ds_read_b128 v[174:177], v174 offset:3072
	s_add_u32 s44, vcc_lo, 0x80000
	s_addc_u32 s45, vcc_hi, 0
	s_mov_b32 m0, s8
	v_lshl_add_u64 v[230:231], s[44:45], 0, v[164:165]
	ds_read_b128 v[178:181], v222 offset:32768
	ds_read_b128 v[182:185], v222 offset:33792
	ds_read_b128 v[186:189], v222 offset:34816
	ds_read_b128 v[190:193], v222 offset:35840
	ds_read_b128 v[204:207], v222 offset:36864
	ds_read_b128 v[208:211], v222 offset:37888
	ds_read_b128 v[212:215], v222 offset:38912
	ds_read_b128 v[216:219], v222 offset:39936
	global_load_lds_dwordx4 v[230:231], off
	v_lshl_add_u64 v[230:231], s[44:45], 0, v[162:163]
	s_mov_b32 m0, s9
	s_nop 0
	global_load_lds_dwordx4 v[230:231], off
	s_waitcnt vmcnt(8)
	s_barrier
	s_setprio 1
	s_waitcnt lgkmcnt(0)
	v_mfma_f32_16x16x32_bf16 v[126:129], v[134:137], v[178:181], v[126:129]
	v_mfma_f32_16x16x32_bf16 v[122:125], v[142:145], v[178:181], v[122:125]
	v_mfma_f32_16x16x32_bf16 v[110:113], v[134:137], v[186:189], v[110:113]
	v_mfma_f32_16x16x32_bf16 v[106:109], v[142:145], v[186:189], v[106:109]
	v_mfma_f32_16x16x32_bf16 v[94:97], v[134:137], v[204:207], v[94:97]
	v_mfma_f32_16x16x32_bf16 v[90:93], v[142:145], v[204:207], v[90:93]
	v_mfma_f32_16x16x32_bf16 v[78:81], v[134:137], v[212:215], v[78:81]
	v_mfma_f32_16x16x32_bf16 v[74:77], v[142:145], v[212:215], v[74:77]
	v_mfma_f32_16x16x32_bf16 v[126:129], v[138:141], v[182:185], v[126:129]
	v_mfma_f32_16x16x32_bf16 v[122:125], v[146:149], v[182:185], v[122:125]
	v_mfma_f32_16x16x32_bf16 v[110:113], v[138:141], v[190:193], v[110:113]
	v_mfma_f32_16x16x32_bf16 v[106:109], v[146:149], v[190:193], v[106:109]
	v_mfma_f32_16x16x32_bf16 v[94:97], v[138:141], v[208:211], v[94:97]
	v_mfma_f32_16x16x32_bf16 v[90:93], v[146:149], v[208:211], v[90:93]
	v_mfma_f32_16x16x32_bf16 v[78:81], v[138:141], v[216:219], v[78:81]
	v_mfma_f32_16x16x32_bf16 v[74:77], v[146:149], v[216:219], v[74:77]
	s_setprio 0
	s_setprio 1
	v_mfma_f32_16x16x32_bf16 v[118:121], v[150:153], v[178:181], v[118:121]
	v_mfma_f32_16x16x32_bf16 v[114:117], v[158:161], v[178:181], v[114:117]
	v_mfma_f32_16x16x32_bf16 v[102:105], v[150:153], v[186:189], v[102:105]
	v_mfma_f32_16x16x32_bf16 v[98:101], v[158:161], v[186:189], v[98:101]
	v_mfma_f32_16x16x32_bf16 v[86:89], v[150:153], v[204:207], v[86:89]
	v_mfma_f32_16x16x32_bf16 v[82:85], v[158:161], v[204:207], v[82:85]
	v_mfma_f32_16x16x32_bf16 v[70:73], v[150:153], v[212:215], v[70:73]
	v_mfma_f32_16x16x32_bf16 v[66:69], v[158:161], v[212:215], v[66:69]
	v_mfma_f32_16x16x32_bf16 v[118:121], v[154:157], v[182:185], v[118:121]
	v_mfma_f32_16x16x32_bf16 v[114:117], v[174:177], v[182:185], v[114:117]
	v_mfma_f32_16x16x32_bf16 v[102:105], v[154:157], v[190:193], v[102:105]
	v_mfma_f32_16x16x32_bf16 v[98:101], v[174:177], v[190:193], v[98:101]
	v_mfma_f32_16x16x32_bf16 v[86:89], v[154:157], v[208:211], v[86:89]
	v_mfma_f32_16x16x32_bf16 v[82:85], v[174:177], v[208:211], v[82:85]
	v_mfma_f32_16x16x32_bf16 v[70:73], v[154:157], v[216:219], v[70:73]
	v_mfma_f32_16x16x32_bf16 v[66:69], v[174:177], v[216:219], v[66:69]
	s_setprio 0
	s_barrier
	s_add_i32 s0, s0, s54
	v_lshl_add_u64 v[220:221], v[220:221], 0, s[82:83]
	s_mov_b32 m0, s0
	ds_read_b128 v[178:181], v222 offset:49152
	ds_read_b128 v[182:185], v222 offset:50176
	ds_read_b128 v[186:189], v222 offset:51200
	ds_read_b128 v[190:193], v222 offset:52224
	ds_read_b128 v[204:207], v222 offset:53248
	ds_read_b128 v[208:211], v222 offset:54272
	ds_read_b128 v[212:215], v222 offset:55296
	ds_read_b128 v[216:219], v222 offset:56320
	global_load_lds_dwordx4 v[220:221], off
	s_add_i32 m0, s0, 0x2000
	s_add_u32 s44, s70, 0x80080
	v_lshl_add_u64 v[220:221], v[224:225], 0, s[82:83]
	s_addc_u32 s45, s71, 0
	s_add_i32 s0, s1, s54
	global_load_lds_dwordx4 v[220:221], off
	v_lshl_add_u64 v[220:221], s[44:45], 0, v[164:165]
	s_mov_b32 m0, s0
	s_nop 0
	global_load_lds_dwordx4 v[220:221], off
	v_lshl_add_u64 v[220:221], s[44:45], 0, v[162:163]
	s_add_i32 m0, s0, 0x2000
	s_nop 0
	global_load_lds_dwordx4 v[220:221], off
	v_lshl_add_u64 v[220:221], v[226:227], 0, s[82:83]
	s_mov_b32 m0, s27
	s_nop 0
	global_load_lds_dwordx4 v[220:221], off
	v_lshl_add_u64 v[220:221], v[228:229], 0, s[82:83]
	s_mov_b32 m0, s26
	s_nop 0
	global_load_lds_dwordx4 v[220:221], off
	s_waitcnt vmcnt(8)
	s_barrier
	s_setprio 1
	s_waitcnt lgkmcnt(0)
	v_mfma_f32_16x16x32_bf16 v[62:65], v[134:137], v[178:181], v[62:65]
	v_mfma_f32_16x16x32_bf16 v[58:61], v[142:145], v[178:181], v[58:61]
	v_mfma_f32_16x16x32_bf16 v[46:49], v[134:137], v[186:189], v[46:49]
	v_mfma_f32_16x16x32_bf16 v[42:45], v[142:145], v[186:189], v[42:45]
	v_mfma_f32_16x16x32_bf16 v[30:33], v[134:137], v[204:207], v[30:33]
	v_mfma_f32_16x16x32_bf16 v[26:29], v[142:145], v[204:207], v[26:29]
	v_mfma_f32_16x16x32_bf16 v[14:17], v[134:137], v[212:215], v[14:17]
	v_mfma_f32_16x16x32_bf16 v[10:13], v[142:145], v[212:215], v[10:13]
	v_mfma_f32_16x16x32_bf16 v[62:65], v[138:141], v[182:185], v[62:65]
	v_mfma_f32_16x16x32_bf16 v[58:61], v[146:149], v[182:185], v[58:61]
	v_mfma_f32_16x16x32_bf16 v[46:49], v[138:141], v[190:193], v[46:49]
	v_mfma_f32_16x16x32_bf16 v[42:45], v[146:149], v[190:193], v[42:45]
	v_mfma_f32_16x16x32_bf16 v[30:33], v[138:141], v[208:211], v[30:33]
	v_mfma_f32_16x16x32_bf16 v[26:29], v[146:149], v[208:211], v[26:29]
	v_mfma_f32_16x16x32_bf16 v[14:17], v[138:141], v[216:219], v[14:17]
	v_mfma_f32_16x16x32_bf16 v[10:13], v[146:149], v[216:219], v[10:13]
	s_setprio 0
	s_setprio 1
	v_mfma_f32_16x16x32_bf16 v[54:57], v[150:153], v[178:181], v[54:57]
	v_mfma_f32_16x16x32_bf16 v[50:53], v[158:161], v[178:181], v[50:53]
	v_mfma_f32_16x16x32_bf16 v[38:41], v[150:153], v[186:189], v[38:41]
	v_mfma_f32_16x16x32_bf16 v[34:37], v[158:161], v[186:189], v[34:37]
	v_mfma_f32_16x16x32_bf16 v[22:25], v[150:153], v[204:207], v[22:25]
	v_mfma_f32_16x16x32_bf16 v[18:21], v[158:161], v[204:207], v[18:21]
	v_mfma_f32_16x16x32_bf16 v[6:9], v[150:153], v[212:215], v[6:9]
	v_mfma_f32_16x16x32_bf16 v[2:5], v[158:161], v[212:215], v[2:5]
	v_mfma_f32_16x16x32_bf16 v[54:57], v[154:157], v[182:185], v[54:57]
	v_mfma_f32_16x16x32_bf16 v[50:53], v[174:177], v[182:185], v[50:53]
	v_mfma_f32_16x16x32_bf16 v[38:41], v[154:157], v[190:193], v[38:41]
	v_mfma_f32_16x16x32_bf16 v[34:37], v[174:177], v[190:193], v[34:37]
	v_mfma_f32_16x16x32_bf16 v[22:25], v[154:157], v[208:211], v[22:25]
	v_mfma_f32_16x16x32_bf16 v[18:21], v[174:177], v[208:211], v[18:21]
	v_mfma_f32_16x16x32_bf16 v[6:9], v[154:157], v[216:219], v[6:9]
	v_mfma_f32_16x16x32_bf16 v[2:5], v[174:177], v[216:219], v[2:5]
	s_setprio 0
	s_barrier
	s_add_i32 s43, s43, 2
	s_add_u32 s76, s76, 0x100
	s_addc_u32 s77, s77, 0
	s_add_u32 s7, s7, 0x100
	s_addc_u32 s41, s41, 0
	s_cmp_gt_u32 s43, 29
	s_cbranch_scc1 .LBB0_288

.LBB0_509:
	s_add_u32 s90, s76, 0x100
	s_addc_u32 s91, s77, 0
	s_and_b64 s[0:1], s[70:71], exec
	s_cselect_b32 vcc_hi, s22, s91
	s_cselect_b32 vcc_lo, s23, s90
	s_cselect_b32 s71, s41, s53
	s_cselect_b32 s70, s44, s51
	s_add_i32 s0, 0, 0x10000
	s_add_i32 s18, 0, 0x14000
	v_add_u32_e32 v114, s0, v1
	v_add_u32_e32 v154, s18, v1
	ds_read_b128 v[78:81], v114
	ds_read_b128 v[90:93], v114 offset:1024
	ds_read_b128 v[102:105], v114 offset:2048
	ds_read_b128 v[114:117], v114 offset:3072
	ds_read_b128 v[126:129], v154
	ds_read_b128 v[134:137], v154 offset:1024
	ds_read_b128 v[142:145], v154 offset:2048
	ds_read_b128 v[154:157], v154 offset:3072
	v_lshl_add_u64 v[218:219], s[76:77], 0, v[210:211]
	s_add_i32 m0, s29, 0xc000
	ds_read_b128 v[158:161], v237
	ds_read_b128 v[162:165], v237 offset:1024
	ds_read_b128 v[166:169], v237 offset:2048
	ds_read_b128 v[178:181], v237 offset:3072
	ds_read_b128 v[182:185], v237 offset:4096
	ds_read_b128 v[186:189], v237 offset:5120
	ds_read_b128 v[190:193], v237 offset:6144
	ds_read_b128 v[214:217], v237 offset:7168
	global_load_lds_dwordx4 v[218:219], off
	v_lshl_add_u64 v[218:219], s[76:77], 0, v[212:213]
	s_add_i32 m0, s29, 0xe000
	s_nop 0
	global_load_lds_dwordx4 v[218:219], off
	s_waitcnt vmcnt(8)
	s_barrier
	s_setprio 1
	s_waitcnt lgkmcnt(0)
	v_mfma_f32_16x16x32_bf16 v[174:177], v[78:81], v[158:161], v[174:177]
	v_mfma_f32_16x16x32_bf16 v[170:173], v[102:105], v[158:161], v[170:173]
	v_mfma_f32_16x16x32_bf16 v[138:141], v[78:81], v[166:169], v[138:141]
	v_mfma_f32_16x16x32_bf16 v[130:133], v[102:105], v[166:169], v[130:133]
	v_mfma_f32_16x16x32_bf16 v[110:113], v[78:81], v[182:185], v[110:113]
	v_mfma_f32_16x16x32_bf16 v[106:109], v[102:105], v[182:185], v[106:109]
	v_mfma_f32_16x16x32_bf16 v[86:89], v[78:81], v[190:193], v[86:89]
	v_mfma_f32_16x16x32_bf16 v[82:85], v[102:105], v[190:193], v[82:85]
	v_mfma_f32_16x16x32_bf16 v[174:177], v[90:93], v[162:165], v[174:177]
	v_mfma_f32_16x16x32_bf16 v[170:173], v[114:117], v[162:165], v[170:173]
	v_mfma_f32_16x16x32_bf16 v[138:141], v[90:93], v[178:181], v[138:141]
	v_mfma_f32_16x16x32_bf16 v[130:133], v[114:117], v[178:181], v[130:133]
	v_mfma_f32_16x16x32_bf16 v[110:113], v[90:93], v[186:189], v[110:113]
	v_mfma_f32_16x16x32_bf16 v[106:109], v[114:117], v[186:189], v[106:109]
	v_mfma_f32_16x16x32_bf16 v[86:89], v[90:93], v[214:217], v[86:89]
	v_mfma_f32_16x16x32_bf16 v[82:85], v[114:117], v[214:217], v[82:85]
	s_setprio 0
	s_setprio 1
	v_mfma_f32_16x16x32_bf16 v[150:153], v[126:129], v[158:161], v[150:153]
	v_mfma_f32_16x16x32_bf16 v[146:149], v[142:145], v[158:161], v[146:149]
	v_mfma_f32_16x16x32_bf16 v[122:125], v[126:129], v[166:169], v[122:125]
	v_mfma_f32_16x16x32_bf16 v[118:121], v[142:145], v[166:169], v[118:121]
	v_mfma_f32_16x16x32_bf16 v[98:101], v[126:129], v[182:185], v[98:101]
	v_mfma_f32_16x16x32_bf16 v[94:97], v[142:145], v[182:185], v[94:97]
	v_mfma_f32_16x16x32_bf16 v[74:77], v[126:129], v[190:193], v[74:77]
	v_mfma_f32_16x16x32_bf16 v[66:69], v[142:145], v[190:193], v[66:69]
	v_mfma_f32_16x16x32_bf16 v[150:153], v[134:137], v[162:165], v[150:153]
	v_mfma_f32_16x16x32_bf16 v[146:149], v[154:157], v[162:165], v[146:149]
	v_mfma_f32_16x16x32_bf16 v[122:125], v[134:137], v[178:181], v[122:125]
	v_mfma_f32_16x16x32_bf16 v[118:121], v[154:157], v[178:181], v[118:121]
	v_mfma_f32_16x16x32_bf16 v[98:101], v[134:137], v[186:189], v[98:101]
	v_mfma_f32_16x16x32_bf16 v[94:97], v[154:157], v[186:189], v[94:97]
	v_mfma_f32_16x16x32_bf16 v[74:77], v[134:137], v[214:217], v[74:77]
	v_mfma_f32_16x16x32_bf16 v[66:69], v[154:157], v[214:217], v[66:69]
	s_setprio 0
	s_barrier
	s_add_i32 s0, s0, s28
	v_lshl_add_u64 v[218:219], s[70:71], 0, v[194:195]
	s_mov_b32 m0, s0
	ds_read_b128 v[158:161], v237 offset:16384
	ds_read_b128 v[162:165], v237 offset:17408
	ds_read_b128 v[166:169], v237 offset:18432
	ds_read_b128 v[178:181], v237 offset:19456
	ds_read_b128 v[182:185], v237 offset:20480
	ds_read_b128 v[186:189], v237 offset:21504
	ds_read_b128 v[190:193], v237 offset:22528
	ds_read_b128 v[214:217], v237 offset:23552
	global_load_lds_dwordx4 v[218:219], off
	s_add_i32 m0, s0, 0x2000
	s_add_u32 s0, s70, 0x80000
	v_lshl_add_u64 v[220:221], s[70:71], 0, v[204:205]
	s_addc_u32 s1, s71, 0
	s_add_i32 s18, s18, s28
	global_load_lds_dwordx4 v[220:221], off
	v_lshl_add_u64 v[222:223], s[0:1], 0, v[194:195]
	s_mov_b32 m0, s18
	v_lshl_add_u64 v[224:225], vcc, 0, v[204:205]
	global_load_lds_dwordx4 v[222:223], off
	v_lshl_add_u64 v[222:223], s[0:1], 0, v[204:205]
	s_add_i32 m0, s18, 0x2000
	s_nop 0
	global_load_lds_dwordx4 v[222:223], off
	v_lshl_add_u64 v[222:223], vcc, 0, v[194:195]
	s_mov_b32 m0, s29
	s_nop 0
	global_load_lds_dwordx4 v[222:223], off
	s_mov_b32 m0, s31
	s_nop 0
	global_load_lds_dwordx4 v[224:225], off
	s_waitcnt vmcnt(8)
	s_barrier
	s_setprio 1
	s_waitcnt lgkmcnt(0)
	v_mfma_f32_16x16x32_bf16 v[62:65], v[78:81], v[158:161], v[62:65]
	v_mfma_f32_16x16x32_bf16 v[58:61], v[102:105], v[158:161], v[58:61]
	v_mfma_f32_16x16x32_bf16 v[46:49], v[78:81], v[166:169], v[46:49]
	v_mfma_f32_16x16x32_bf16 v[42:45], v[102:105], v[166:169], v[42:45]
	v_mfma_f32_16x16x32_bf16 v[30:33], v[78:81], v[182:185], v[30:33]
	v_mfma_f32_16x16x32_bf16 v[26:29], v[102:105], v[182:185], v[26:29]
	v_mfma_f32_16x16x32_bf16 v[14:17], v[78:81], v[190:193], v[14:17]
	v_mfma_f32_16x16x32_bf16 v[10:13], v[102:105], v[190:193], v[10:13]
	v_mfma_f32_16x16x32_bf16 v[62:65], v[90:93], v[162:165], v[62:65]
	v_mfma_f32_16x16x32_bf16 v[58:61], v[114:117], v[162:165], v[58:61]
	v_mfma_f32_16x16x32_bf16 v[46:49], v[90:93], v[178:181], v[46:49]
	v_mfma_f32_16x16x32_bf16 v[42:45], v[114:117], v[178:181], v[42:45]
	v_mfma_f32_16x16x32_bf16 v[30:33], v[90:93], v[186:189], v[30:33]
	v_mfma_f32_16x16x32_bf16 v[26:29], v[114:117], v[186:189], v[26:29]
	v_mfma_f32_16x16x32_bf16 v[14:17], v[90:93], v[214:217], v[14:17]
	v_mfma_f32_16x16x32_bf16 v[10:13], v[114:117], v[214:217], v[10:13]
	s_setprio 0
	s_setprio 1
	v_mfma_f32_16x16x32_bf16 v[54:57], v[126:129], v[158:161], v[54:57]
	v_mfma_f32_16x16x32_bf16 v[50:53], v[142:145], v[158:161], v[50:53]
	v_mfma_f32_16x16x32_bf16 v[38:41], v[126:129], v[166:169], v[38:41]
	v_mfma_f32_16x16x32_bf16 v[34:37], v[142:145], v[166:169], v[34:37]
	v_mfma_f32_16x16x32_bf16 v[22:25], v[126:129], v[182:185], v[22:25]
	v_mfma_f32_16x16x32_bf16 v[18:21], v[142:145], v[182:185], v[18:21]
	v_mfma_f32_16x16x32_bf16 v[6:9], v[126:129], v[190:193], v[6:9]
	v_mfma_f32_16x16x32_bf16 v[2:5], v[142:145], v[190:193], v[2:5]
	v_mfma_f32_16x16x32_bf16 v[54:57], v[134:137], v[162:165], v[54:57]
	v_mfma_f32_16x16x32_bf16 v[50:53], v[154:157], v[162:165], v[50:53]
	v_mfma_f32_16x16x32_bf16 v[38:41], v[134:137], v[178:181], v[38:41]
	v_mfma_f32_16x16x32_bf16 v[34:37], v[154:157], v[178:181], v[34:37]
	v_mfma_f32_16x16x32_bf16 v[22:25], v[134:137], v[186:189], v[22:25]
	v_mfma_f32_16x16x32_bf16 v[18:21], v[154:157], v[186:189], v[18:21]
	v_mfma_f32_16x16x32_bf16 v[6:9], v[134:137], v[214:217], v[6:9]
	v_mfma_f32_16x16x32_bf16 v[2:5], v[154:157], v[214:217], v[2:5]
	s_setprio 0
	s_barrier
	s_add_i32 s18, 0, 0x18000
	s_add_i32 s19, 0, 0x1c000
	v_add_u32_e32 v114, s18, v1
	v_add_u32_e32 v154, s19, v1
	ds_read_b128 v[78:81], v114
	ds_read_b128 v[90:93], v114 offset:1024
	ds_read_b128 v[102:105], v114 offset:2048
	ds_read_b128 v[114:117], v114 offset:3072
	ds_read_b128 v[126:129], v154
	ds_read_b128 v[134:137], v154 offset:1024
	ds_read_b128 v[142:145], v154 offset:2048
	ds_read_b128 v[154:157], v154 offset:3072
	s_add_u32 s0, vcc_lo, 0x80000
	s_addc_u32 s1, vcc_hi, 0
	s_mov_b32 m0, s33
	v_lshl_add_u64 v[226:227], s[0:1], 0, v[194:195]
	ds_read_b128 v[158:161], v237 offset:32768
	ds_read_b128 v[162:165], v237 offset:33792
	ds_read_b128 v[166:169], v237 offset:34816
	ds_read_b128 v[178:181], v237 offset:35840
	ds_read_b128 v[182:185], v237 offset:36864
	ds_read_b128 v[186:189], v237 offset:37888
	ds_read_b128 v[190:193], v237 offset:38912
	ds_read_b128 v[214:217], v237 offset:39936
	global_load_lds_dwordx4 v[226:227], off
	v_lshl_add_u64 v[226:227], s[0:1], 0, v[204:205]
	s_mov_b32 m0, s43
	s_nop 0
	global_load_lds_dwordx4 v[226:227], off
	s_waitcnt vmcnt(8)
	s_barrier
	s_setprio 1
	s_waitcnt lgkmcnt(0)
	v_mfma_f32_16x16x32_bf16 v[174:177], v[78:81], v[158:161], v[174:177]
	v_mfma_f32_16x16x32_bf16 v[170:173], v[102:105], v[158:161], v[170:173]
	v_mfma_f32_16x16x32_bf16 v[138:141], v[78:81], v[166:169], v[138:141]
	v_mfma_f32_16x16x32_bf16 v[130:133], v[102:105], v[166:169], v[130:133]
	v_mfma_f32_16x16x32_bf16 v[110:113], v[78:81], v[182:185], v[110:113]
	v_mfma_f32_16x16x32_bf16 v[106:109], v[102:105], v[182:185], v[106:109]
	v_mfma_f32_16x16x32_bf16 v[86:89], v[78:81], v[190:193], v[86:89]
	v_mfma_f32_16x16x32_bf16 v[82:85], v[102:105], v[190:193], v[82:85]
	v_mfma_f32_16x16x32_bf16 v[174:177], v[90:93], v[162:165], v[174:177]
	v_mfma_f32_16x16x32_bf16 v[170:173], v[114:117], v[162:165], v[170:173]
	v_mfma_f32_16x16x32_bf16 v[138:141], v[90:93], v[178:181], v[138:141]
	v_mfma_f32_16x16x32_bf16 v[130:133], v[114:117], v[178:181], v[130:133]
	v_mfma_f32_16x16x32_bf16 v[110:113], v[90:93], v[186:189], v[110:113]
	v_mfma_f32_16x16x32_bf16 v[106:109], v[114:117], v[186:189], v[106:109]
	v_mfma_f32_16x16x32_bf16 v[86:89], v[90:93], v[214:217], v[86:89]
	v_mfma_f32_16x16x32_bf16 v[82:85], v[114:117], v[214:217], v[82:85]
	s_setprio 0
	s_setprio 1
	v_mfma_f32_16x16x32_bf16 v[150:153], v[126:129], v[158:161], v[150:153]
	v_mfma_f32_16x16x32_bf16 v[146:149], v[142:145], v[158:161], v[146:149]
	v_mfma_f32_16x16x32_bf16 v[122:125], v[126:129], v[166:169], v[122:125]
	v_mfma_f32_16x16x32_bf16 v[118:121], v[142:145], v[166:169], v[118:121]
	v_mfma_f32_16x16x32_bf16 v[98:101], v[126:129], v[182:185], v[98:101]
	v_mfma_f32_16x16x32_bf16 v[94:97], v[142:145], v[182:185], v[94:97]
	v_mfma_f32_16x16x32_bf16 v[74:77], v[126:129], v[190:193], v[74:77]
	v_mfma_f32_16x16x32_bf16 v[66:69], v[142:145], v[190:193], v[66:69]
	v_mfma_f32_16x16x32_bf16 v[150:153], v[134:137], v[162:165], v[150:153]
	v_mfma_f32_16x16x32_bf16 v[146:149], v[154:157], v[162:165], v[146:149]
	v_mfma_f32_16x16x32_bf16 v[122:125], v[134:137], v[178:181], v[122:125]
	v_mfma_f32_16x16x32_bf16 v[118:121], v[154:157], v[178:181], v[118:121]
	v_mfma_f32_16x16x32_bf16 v[98:101], v[134:137], v[186:189], v[98:101]
	v_mfma_f32_16x16x32_bf16 v[94:97], v[154:157], v[186:189], v[94:97]
	v_mfma_f32_16x16x32_bf16 v[74:77], v[134:137], v[214:217], v[74:77]
	v_mfma_f32_16x16x32_bf16 v[66:69], v[154:157], v[214:217], v[66:69]
	s_setprio 0
	s_barrier
	s_add_i32 s0, s18, s28
	v_lshl_add_u64 v[218:219], v[218:219], 0, s[82:83]
	s_mov_b32 m0, s0
	ds_read_b128 v[158:161], v237 offset:49152
	ds_read_b128 v[162:165], v237 offset:50176
	ds_read_b128 v[166:169], v237 offset:51200
	ds_read_b128 v[178:181], v237 offset:52224
	ds_read_b128 v[182:185], v237 offset:53248
	ds_read_b128 v[186:189], v237 offset:54272
	ds_read_b128 v[190:193], v237 offset:55296
	ds_read_b128 v[214:217], v237 offset:56320
	global_load_lds_dwordx4 v[218:219], off
	s_add_i32 m0, s0, 0x2000
	s_add_u32 s0, s70, 0x80080
	v_lshl_add_u64 v[218:219], v[220:221], 0, s[82:83]
	s_addc_u32 s1, s71, 0
	s_add_i32 s18, s19, s28
	global_load_lds_dwordx4 v[218:219], off
	v_lshl_add_u64 v[218:219], s[0:1], 0, v[194:195]
	s_mov_b32 m0, s18
	s_nop 0
	global_load_lds_dwordx4 v[218:219], off
	v_lshl_add_u64 v[218:219], s[0:1], 0, v[204:205]
	s_add_i32 m0, s18, 0x2000
	s_nop 0
	global_load_lds_dwordx4 v[218:219], off
	v_lshl_add_u64 v[218:219], v[222:223], 0, s[82:83]
	s_mov_b32 m0, s68
	s_nop 0
	global_load_lds_dwordx4 v[218:219], off
	v_lshl_add_u64 v[218:219], v[224:225], 0, s[82:83]
	s_mov_b32 m0, s79
	s_nop 0
	global_load_lds_dwordx4 v[218:219], off
	s_waitcnt vmcnt(8)
	s_barrier
	s_setprio 1
	s_waitcnt lgkmcnt(0)
	v_mfma_f32_16x16x32_bf16 v[62:65], v[78:81], v[158:161], v[62:65]
	v_mfma_f32_16x16x32_bf16 v[58:61], v[102:105], v[158:161], v[58:61]
	v_mfma_f32_16x16x32_bf16 v[46:49], v[78:81], v[166:169], v[46:49]
	v_mfma_f32_16x16x32_bf16 v[42:45], v[102:105], v[166:169], v[42:45]
	v_mfma_f32_16x16x32_bf16 v[30:33], v[78:81], v[182:185], v[30:33]
	v_mfma_f32_16x16x32_bf16 v[26:29], v[102:105], v[182:185], v[26:29]
	v_mfma_f32_16x16x32_bf16 v[14:17], v[78:81], v[190:193], v[14:17]
	v_mfma_f32_16x16x32_bf16 v[10:13], v[102:105], v[190:193], v[10:13]
	v_mfma_f32_16x16x32_bf16 v[62:65], v[90:93], v[162:165], v[62:65]
	v_mfma_f32_16x16x32_bf16 v[58:61], v[114:117], v[162:165], v[58:61]
	v_mfma_f32_16x16x32_bf16 v[46:49], v[90:93], v[178:181], v[46:49]
	v_mfma_f32_16x16x32_bf16 v[42:45], v[114:117], v[178:181], v[42:45]
	v_mfma_f32_16x16x32_bf16 v[30:33], v[90:93], v[186:189], v[30:33]
	v_mfma_f32_16x16x32_bf16 v[26:29], v[114:117], v[186:189], v[26:29]
	v_mfma_f32_16x16x32_bf16 v[14:17], v[90:93], v[214:217], v[14:17]
	v_mfma_f32_16x16x32_bf16 v[10:13], v[114:117], v[214:217], v[10:13]
	s_setprio 0
	s_setprio 1
	v_mfma_f32_16x16x32_bf16 v[54:57], v[126:129], v[158:161], v[54:57]
	v_mfma_f32_16x16x32_bf16 v[50:53], v[142:145], v[158:161], v[50:53]
	v_mfma_f32_16x16x32_bf16 v[38:41], v[126:129], v[166:169], v[38:41]
	v_mfma_f32_16x16x32_bf16 v[34:37], v[142:145], v[166:169], v[34:37]
	v_mfma_f32_16x16x32_bf16 v[22:25], v[126:129], v[182:185], v[22:25]
	v_mfma_f32_16x16x32_bf16 v[18:21], v[142:145], v[182:185], v[18:21]
	v_mfma_f32_16x16x32_bf16 v[6:9], v[126:129], v[190:193], v[6:9]
	v_mfma_f32_16x16x32_bf16 v[2:5], v[142:145], v[190:193], v[2:5]
	v_mfma_f32_16x16x32_bf16 v[54:57], v[134:137], v[162:165], v[54:57]
	v_mfma_f32_16x16x32_bf16 v[50:53], v[154:157], v[162:165], v[50:53]
	v_mfma_f32_16x16x32_bf16 v[38:41], v[134:137], v[178:181], v[38:41]
	v_mfma_f32_16x16x32_bf16 v[34:37], v[154:157], v[178:181], v[34:37]
	v_mfma_f32_16x16x32_bf16 v[22:25], v[134:137], v[186:189], v[22:25]
	v_mfma_f32_16x16x32_bf16 v[18:21], v[154:157], v[186:189], v[18:21]
	v_mfma_f32_16x16x32_bf16 v[6:9], v[134:137], v[214:217], v[6:9]
	v_mfma_f32_16x16x32_bf16 v[2:5], v[154:157], v[214:217], v[2:5]
	s_setprio 0
	s_barrier
	s_add_i32 s57, s57, 2
	s_add_u32 s51, s51, 0x100
	s_addc_u32 s53, s53, 0
	s_cmp_gt_u32 s57, 29
	s_mov_b64 s[76:77], s[90:91]
	s_cbranch_scc1 .LBB0_512

.LBB0_581:
	s_add_u32 s18, s62, 0xfff80080
	s_addc_u32 s19, s63, -1
	s_and_b64 s[0:1], s[64:65], exec
	s_cselect_b32 s71, s22, s19
	s_cselect_b32 s70, s23, s18
	s_cselect_b32 s65, s39, s58
	s_cselect_b32 s64, s47, s53
	s_add_i32 s0, 0, 0x10000
	v_add_u32_e32 v153, s0, v1
	s_add_i32 s18, 0, 0x14000
	ds_read_b128 v[144:147], v153
	ds_read_b128 v[148:151], v153 offset:1024
	ds_read_b128 v[154:157], v153 offset:2048
	ds_read_b128 v[158:161], v153 offset:3072
	v_add_u32_e32 v153, s18, v1
	ds_read_b128 v[162:165], v153
	ds_read_b128 v[166:169], v153 offset:1024
	ds_read_b128 v[170:173], v153 offset:2048
	ds_read_b128 v[174:177], v153 offset:3072
	v_lshl_add_u64 v[220:221], s[62:63], 0, v[136:137]
	s_add_i32 m0, s29, 0xc000
	ds_read_b128 v[178:181], v152
	ds_read_b128 v[182:185], v152 offset:1024
	ds_read_b128 v[186:189], v152 offset:2048
	ds_read_b128 v[190:193], v152 offset:3072
	ds_read_b128 v[204:207], v152 offset:4096
	ds_read_b128 v[208:211], v152 offset:5120
	ds_read_b128 v[212:215], v152 offset:6144
	ds_read_b128 v[216:219], v152 offset:7168
	global_load_lds_dwordx4 v[220:221], off
	v_lshl_add_u64 v[220:221], s[62:63], 0, v[138:139]
	s_add_i32 m0, s29, 0xe000
	s_nop 0
	global_load_lds_dwordx4 v[220:221], off
	s_waitcnt vmcnt(8)
	s_barrier
	s_setprio 1
	s_waitcnt lgkmcnt(0)
	v_mfma_f32_16x16x32_bf16 v[126:129], v[144:147], v[178:181], v[126:129]
	v_mfma_f32_16x16x32_bf16 v[122:125], v[154:157], v[178:181], v[122:125]
	v_mfma_f32_16x16x32_bf16 v[110:113], v[144:147], v[186:189], v[110:113]
	v_mfma_f32_16x16x32_bf16 v[106:109], v[154:157], v[186:189], v[106:109]
	v_mfma_f32_16x16x32_bf16 v[94:97], v[144:147], v[204:207], v[94:97]
	v_mfma_f32_16x16x32_bf16 v[90:93], v[154:157], v[204:207], v[90:93]
	v_mfma_f32_16x16x32_bf16 v[78:81], v[144:147], v[212:215], v[78:81]
	v_mfma_f32_16x16x32_bf16 v[74:77], v[154:157], v[212:215], v[74:77]
	v_mfma_f32_16x16x32_bf16 v[126:129], v[148:151], v[182:185], v[126:129]
	v_mfma_f32_16x16x32_bf16 v[122:125], v[158:161], v[182:185], v[122:125]
	v_mfma_f32_16x16x32_bf16 v[110:113], v[148:151], v[190:193], v[110:113]
	v_mfma_f32_16x16x32_bf16 v[106:109], v[158:161], v[190:193], v[106:109]
	v_mfma_f32_16x16x32_bf16 v[94:97], v[148:151], v[208:211], v[94:97]
	v_mfma_f32_16x16x32_bf16 v[90:93], v[158:161], v[208:211], v[90:93]
	v_mfma_f32_16x16x32_bf16 v[78:81], v[148:151], v[216:219], v[78:81]
	v_mfma_f32_16x16x32_bf16 v[74:77], v[158:161], v[216:219], v[74:77]
	s_setprio 0
	s_setprio 1
	v_mfma_f32_16x16x32_bf16 v[118:121], v[162:165], v[178:181], v[118:121]
	v_mfma_f32_16x16x32_bf16 v[114:117], v[170:173], v[178:181], v[114:117]
	v_mfma_f32_16x16x32_bf16 v[102:105], v[162:165], v[186:189], v[102:105]
	v_mfma_f32_16x16x32_bf16 v[98:101], v[170:173], v[186:189], v[98:101]
	v_mfma_f32_16x16x32_bf16 v[86:89], v[162:165], v[204:207], v[86:89]
	v_mfma_f32_16x16x32_bf16 v[82:85], v[170:173], v[204:207], v[82:85]
	v_mfma_f32_16x16x32_bf16 v[70:73], v[162:165], v[212:215], v[70:73]
	v_mfma_f32_16x16x32_bf16 v[66:69], v[170:173], v[212:215], v[66:69]
	v_mfma_f32_16x16x32_bf16 v[118:121], v[166:169], v[182:185], v[118:121]
	v_mfma_f32_16x16x32_bf16 v[114:117], v[174:177], v[182:185], v[114:117]
	v_mfma_f32_16x16x32_bf16 v[102:105], v[166:169], v[190:193], v[102:105]
	v_mfma_f32_16x16x32_bf16 v[98:101], v[174:177], v[190:193], v[98:101]
	v_mfma_f32_16x16x32_bf16 v[86:89], v[166:169], v[208:211], v[86:89]
	v_mfma_f32_16x16x32_bf16 v[82:85], v[174:177], v[208:211], v[82:85]
	v_mfma_f32_16x16x32_bf16 v[70:73], v[166:169], v[216:219], v[70:73]
	v_mfma_f32_16x16x32_bf16 v[66:69], v[174:177], v[216:219], v[66:69]
	s_setprio 0
	s_barrier
	s_add_i32 s0, s0, s28
	v_lshl_add_u64 v[220:221], s[64:65], 0, v[194:195]
	s_mov_b32 m0, s0
	ds_read_b128 v[178:181], v152 offset:16384
	ds_read_b128 v[182:185], v152 offset:17408
	ds_read_b128 v[186:189], v152 offset:18432
	ds_read_b128 v[190:193], v152 offset:19456
	ds_read_b128 v[204:207], v152 offset:20480
	ds_read_b128 v[208:211], v152 offset:21504
	ds_read_b128 v[212:215], v152 offset:22528
	ds_read_b128 v[216:219], v152 offset:23552
	global_load_lds_dwordx4 v[220:221], off
	s_add_i32 m0, s0, 0x2000
	s_add_u32 s0, s64, 0x80000
	v_lshl_add_u64 v[222:223], s[64:65], 0, v[130:131]
	s_addc_u32 s1, s65, 0
	s_add_i32 s18, s18, s28
	global_load_lds_dwordx4 v[222:223], off
	v_lshl_add_u64 v[224:225], s[0:1], 0, v[194:195]
	s_mov_b32 m0, s18
	v_lshl_add_u64 v[226:227], s[70:71], 0, v[130:131]
	global_load_lds_dwordx4 v[224:225], off
	v_lshl_add_u64 v[224:225], s[0:1], 0, v[130:131]
	s_add_i32 m0, s18, 0x2000
	s_nop 0
	global_load_lds_dwordx4 v[224:225], off
	v_lshl_add_u64 v[224:225], s[70:71], 0, v[194:195]
	s_mov_b32 m0, s29
	s_nop 0
	global_load_lds_dwordx4 v[224:225], off
	s_mov_b32 m0, s31
	s_nop 0
	global_load_lds_dwordx4 v[226:227], off
	s_waitcnt vmcnt(8)
	s_barrier
	s_setprio 1
	s_waitcnt lgkmcnt(0)
	v_mfma_f32_16x16x32_bf16 v[62:65], v[144:147], v[178:181], v[62:65]
	v_mfma_f32_16x16x32_bf16 v[58:61], v[154:157], v[178:181], v[58:61]
	v_mfma_f32_16x16x32_bf16 v[46:49], v[144:147], v[186:189], v[46:49]
	v_mfma_f32_16x16x32_bf16 v[42:45], v[154:157], v[186:189], v[42:45]
	v_mfma_f32_16x16x32_bf16 v[30:33], v[144:147], v[204:207], v[30:33]
	v_mfma_f32_16x16x32_bf16 v[26:29], v[154:157], v[204:207], v[26:29]
	v_mfma_f32_16x16x32_bf16 v[14:17], v[144:147], v[212:215], v[14:17]
	v_mfma_f32_16x16x32_bf16 v[10:13], v[154:157], v[212:215], v[10:13]
	v_mfma_f32_16x16x32_bf16 v[62:65], v[148:151], v[182:185], v[62:65]
	v_mfma_f32_16x16x32_bf16 v[58:61], v[158:161], v[182:185], v[58:61]
	v_mfma_f32_16x16x32_bf16 v[46:49], v[148:151], v[190:193], v[46:49]
	v_mfma_f32_16x16x32_bf16 v[42:45], v[158:161], v[190:193], v[42:45]
	v_mfma_f32_16x16x32_bf16 v[30:33], v[148:151], v[208:211], v[30:33]
	v_mfma_f32_16x16x32_bf16 v[26:29], v[158:161], v[208:211], v[26:29]
	v_mfma_f32_16x16x32_bf16 v[14:17], v[148:151], v[216:219], v[14:17]
	v_mfma_f32_16x16x32_bf16 v[10:13], v[158:161], v[216:219], v[10:13]
	s_setprio 0
	s_setprio 1
	v_mfma_f32_16x16x32_bf16 v[54:57], v[162:165], v[178:181], v[54:57]
	v_mfma_f32_16x16x32_bf16 v[50:53], v[170:173], v[178:181], v[50:53]
	v_mfma_f32_16x16x32_bf16 v[38:41], v[162:165], v[186:189], v[38:41]
	v_mfma_f32_16x16x32_bf16 v[34:37], v[170:173], v[186:189], v[34:37]
	v_mfma_f32_16x16x32_bf16 v[22:25], v[162:165], v[204:207], v[22:25]
	v_mfma_f32_16x16x32_bf16 v[18:21], v[170:173], v[204:207], v[18:21]
	v_mfma_f32_16x16x32_bf16 v[6:9], v[162:165], v[212:215], v[6:9]
	v_mfma_f32_16x16x32_bf16 v[2:5], v[170:173], v[212:215], v[2:5]
	v_mfma_f32_16x16x32_bf16 v[54:57], v[166:169], v[182:185], v[54:57]
	v_mfma_f32_16x16x32_bf16 v[50:53], v[174:177], v[182:185], v[50:53]
	v_mfma_f32_16x16x32_bf16 v[38:41], v[166:169], v[190:193], v[38:41]
	v_mfma_f32_16x16x32_bf16 v[34:37], v[174:177], v[190:193], v[34:37]
	v_mfma_f32_16x16x32_bf16 v[22:25], v[166:169], v[208:211], v[22:25]
	v_mfma_f32_16x16x32_bf16 v[18:21], v[174:177], v[208:211], v[18:21]
	v_mfma_f32_16x16x32_bf16 v[6:9], v[166:169], v[216:219], v[6:9]
	v_mfma_f32_16x16x32_bf16 v[2:5], v[174:177], v[216:219], v[2:5]
	s_setprio 0
	s_barrier
	s_add_i32 s18, 0, 0x18000
	v_add_u32_e32 v153, s18, v1
	s_add_i32 s19, 0, 0x1c000
	ds_read_b128 v[144:147], v153
	ds_read_b128 v[148:151], v153 offset:1024
	ds_read_b128 v[154:157], v153 offset:2048
	ds_read_b128 v[158:161], v153 offset:3072
	v_add_u32_e32 v153, s19, v1
	ds_read_b128 v[162:165], v153
	ds_read_b128 v[166:169], v153 offset:1024
	ds_read_b128 v[170:173], v153 offset:2048
	ds_read_b128 v[174:177], v153 offset:3072
	s_add_u32 s0, s70, 0x80000
	s_addc_u32 s1, s71, 0
	s_mov_b32 m0, s33
	v_lshl_add_u64 v[228:229], s[0:1], 0, v[194:195]
	ds_read_b128 v[178:181], v152 offset:32768
	ds_read_b128 v[182:185], v152 offset:33792
	ds_read_b128 v[186:189], v152 offset:34816
	ds_read_b128 v[190:193], v152 offset:35840
	ds_read_b128 v[204:207], v152 offset:36864
	ds_read_b128 v[208:211], v152 offset:37888
	ds_read_b128 v[212:215], v152 offset:38912
	ds_read_b128 v[216:219], v152 offset:39936
	global_load_lds_dwordx4 v[228:229], off
	v_lshl_add_u64 v[228:229], s[0:1], 0, v[130:131]
	s_mov_b32 m0, s40
	s_nop 0
	global_load_lds_dwordx4 v[228:229], off
	s_waitcnt vmcnt(8)
	s_barrier
	s_setprio 1
	s_waitcnt lgkmcnt(0)
	v_mfma_f32_16x16x32_bf16 v[126:129], v[144:147], v[178:181], v[126:129]
	v_mfma_f32_16x16x32_bf16 v[122:125], v[154:157], v[178:181], v[122:125]
	v_mfma_f32_16x16x32_bf16 v[110:113], v[144:147], v[186:189], v[110:113]
	v_mfma_f32_16x16x32_bf16 v[106:109], v[154:157], v[186:189], v[106:109]
	v_mfma_f32_16x16x32_bf16 v[94:97], v[144:147], v[204:207], v[94:97]
	v_mfma_f32_16x16x32_bf16 v[90:93], v[154:157], v[204:207], v[90:93]
	v_mfma_f32_16x16x32_bf16 v[78:81], v[144:147], v[212:215], v[78:81]
	v_mfma_f32_16x16x32_bf16 v[74:77], v[154:157], v[212:215], v[74:77]
	v_mfma_f32_16x16x32_bf16 v[126:129], v[148:151], v[182:185], v[126:129]
	v_mfma_f32_16x16x32_bf16 v[122:125], v[158:161], v[182:185], v[122:125]
	v_mfma_f32_16x16x32_bf16 v[110:113], v[148:151], v[190:193], v[110:113]
	v_mfma_f32_16x16x32_bf16 v[106:109], v[158:161], v[190:193], v[106:109]
	v_mfma_f32_16x16x32_bf16 v[94:97], v[148:151], v[208:211], v[94:97]
	v_mfma_f32_16x16x32_bf16 v[90:93], v[158:161], v[208:211], v[90:93]
	v_mfma_f32_16x16x32_bf16 v[78:81], v[148:151], v[216:219], v[78:81]
	v_mfma_f32_16x16x32_bf16 v[74:77], v[158:161], v[216:219], v[74:77]
	s_setprio 0
	s_setprio 1
	v_mfma_f32_16x16x32_bf16 v[118:121], v[162:165], v[178:181], v[118:121]
	v_mfma_f32_16x16x32_bf16 v[114:117], v[170:173], v[178:181], v[114:117]
	v_mfma_f32_16x16x32_bf16 v[102:105], v[162:165], v[186:189], v[102:105]
	v_mfma_f32_16x16x32_bf16 v[98:101], v[170:173], v[186:189], v[98:101]
	v_mfma_f32_16x16x32_bf16 v[86:89], v[162:165], v[204:207], v[86:89]
	v_mfma_f32_16x16x32_bf16 v[82:85], v[170:173], v[204:207], v[82:85]
	v_mfma_f32_16x16x32_bf16 v[70:73], v[162:165], v[212:215], v[70:73]
	v_mfma_f32_16x16x32_bf16 v[66:69], v[170:173], v[212:215], v[66:69]
	v_mfma_f32_16x16x32_bf16 v[118:121], v[166:169], v[182:185], v[118:121]
	v_mfma_f32_16x16x32_bf16 v[114:117], v[174:177], v[182:185], v[114:117]
	v_mfma_f32_16x16x32_bf16 v[102:105], v[166:169], v[190:193], v[102:105]
	v_mfma_f32_16x16x32_bf16 v[98:101], v[174:177], v[190:193], v[98:101]
	v_mfma_f32_16x16x32_bf16 v[86:89], v[166:169], v[208:211], v[86:89]
	v_mfma_f32_16x16x32_bf16 v[82:85], v[174:177], v[208:211], v[82:85]
	v_mfma_f32_16x16x32_bf16 v[70:73], v[166:169], v[216:219], v[70:73]
	v_mfma_f32_16x16x32_bf16 v[66:69], v[174:177], v[216:219], v[66:69]
	s_setprio 0
	s_barrier
	s_add_i32 s0, s18, s28
	v_lshl_add_u64 v[220:221], v[220:221], 0, s[82:83]
	s_mov_b32 m0, s0
	ds_read_b128 v[178:181], v152 offset:49152
	ds_read_b128 v[182:185], v152 offset:50176
	ds_read_b128 v[186:189], v152 offset:51200
	ds_read_b128 v[190:193], v152 offset:52224
	ds_read_b128 v[204:207], v152 offset:53248
	ds_read_b128 v[208:211], v152 offset:54272
	ds_read_b128 v[212:215], v152 offset:55296
	ds_read_b128 v[216:219], v152 offset:56320
	global_load_lds_dwordx4 v[220:221], off
	s_add_i32 m0, s0, 0x2000
	s_add_u32 s0, s64, 0x80080
	v_lshl_add_u64 v[220:221], v[222:223], 0, s[82:83]
	s_addc_u32 s1, s65, 0
	s_add_i32 s18, s19, s28
	global_load_lds_dwordx4 v[220:221], off
	v_lshl_add_u64 v[220:221], s[0:1], 0, v[194:195]
	s_mov_b32 m0, s18
	s_nop 0
	global_load_lds_dwordx4 v[220:221], off
	v_lshl_add_u64 v[220:221], s[0:1], 0, v[130:131]
	s_add_i32 m0, s18, 0x2000
	s_nop 0
	global_load_lds_dwordx4 v[220:221], off
	v_lshl_add_u64 v[220:221], v[224:225], 0, s[82:83]
	s_mov_b32 m0, s54
	s_nop 0
	global_load_lds_dwordx4 v[220:221], off
	v_lshl_add_u64 v[220:221], v[226:227], 0, s[82:83]
	s_mov_b32 m0, s57
	s_nop 0
	global_load_lds_dwordx4 v[220:221], off
	s_waitcnt vmcnt(8)
	s_barrier
	s_setprio 1
	s_waitcnt lgkmcnt(0)
	v_mfma_f32_16x16x32_bf16 v[62:65], v[144:147], v[178:181], v[62:65]
	v_mfma_f32_16x16x32_bf16 v[58:61], v[154:157], v[178:181], v[58:61]
	v_mfma_f32_16x16x32_bf16 v[46:49], v[144:147], v[186:189], v[46:49]
	v_mfma_f32_16x16x32_bf16 v[42:45], v[154:157], v[186:189], v[42:45]
	v_mfma_f32_16x16x32_bf16 v[30:33], v[144:147], v[204:207], v[30:33]
	v_mfma_f32_16x16x32_bf16 v[26:29], v[154:157], v[204:207], v[26:29]
	v_mfma_f32_16x16x32_bf16 v[14:17], v[144:147], v[212:215], v[14:17]
	v_mfma_f32_16x16x32_bf16 v[10:13], v[154:157], v[212:215], v[10:13]
	v_mfma_f32_16x16x32_bf16 v[62:65], v[148:151], v[182:185], v[62:65]
	v_mfma_f32_16x16x32_bf16 v[58:61], v[158:161], v[182:185], v[58:61]
	v_mfma_f32_16x16x32_bf16 v[46:49], v[148:151], v[190:193], v[46:49]
	v_mfma_f32_16x16x32_bf16 v[42:45], v[158:161], v[190:193], v[42:45]
	v_mfma_f32_16x16x32_bf16 v[30:33], v[148:151], v[208:211], v[30:33]
	v_mfma_f32_16x16x32_bf16 v[26:29], v[158:161], v[208:211], v[26:29]
	v_mfma_f32_16x16x32_bf16 v[14:17], v[148:151], v[216:219], v[14:17]
	v_mfma_f32_16x16x32_bf16 v[10:13], v[158:161], v[216:219], v[10:13]
	s_setprio 0
	s_setprio 1
	v_mfma_f32_16x16x32_bf16 v[54:57], v[162:165], v[178:181], v[54:57]
	v_mfma_f32_16x16x32_bf16 v[50:53], v[170:173], v[178:181], v[50:53]
	v_mfma_f32_16x16x32_bf16 v[38:41], v[162:165], v[186:189], v[38:41]
	v_mfma_f32_16x16x32_bf16 v[34:37], v[170:173], v[186:189], v[34:37]
	v_mfma_f32_16x16x32_bf16 v[22:25], v[162:165], v[204:207], v[22:25]
	v_mfma_f32_16x16x32_bf16 v[18:21], v[170:173], v[204:207], v[18:21]
	v_mfma_f32_16x16x32_bf16 v[6:9], v[162:165], v[212:215], v[6:9]
	v_mfma_f32_16x16x32_bf16 v[2:5], v[170:173], v[212:215], v[2:5]
	v_mfma_f32_16x16x32_bf16 v[54:57], v[166:169], v[182:185], v[54:57]
	v_mfma_f32_16x16x32_bf16 v[50:53], v[174:177], v[182:185], v[50:53]
	v_mfma_f32_16x16x32_bf16 v[38:41], v[166:169], v[190:193], v[38:41]
	v_mfma_f32_16x16x32_bf16 v[34:37], v[174:177], v[190:193], v[34:37]
	v_mfma_f32_16x16x32_bf16 v[22:25], v[166:169], v[208:211], v[22:25]
	v_mfma_f32_16x16x32_bf16 v[18:21], v[174:177], v[208:211], v[18:21]
	v_mfma_f32_16x16x32_bf16 v[6:9], v[166:169], v[216:219], v[6:9]
	v_mfma_f32_16x16x32_bf16 v[2:5], v[174:177], v[216:219], v[2:5]
	s_setprio 0
	s_barrier
	s_add_i32 s76, s76, 2
	s_add_u32 s62, s62, 0x100
	s_addc_u32 s63, s63, 0
	s_add_u32 s53, s53, 0x100
	s_addc_u32 s58, s58, 0
	s_cmp_gt_u32 s76, 29
	s_cbranch_scc1 .LBB0_584

.LBB0_645:
	s_add_u32 s64, s8, 0x100
	s_addc_u32 s65, s9, 0
	s_and_b64 s[0:1], s[70:71], exec
	s_cselect_b32 s77, s63, s65
	s_cselect_b32 s76, s62, s64
	s_cselect_b32 s71, s85, s23
	s_cselect_b32 s70, s84, s7
	s_add_i32 s0, 0, 0x10000
	s_add_i32 s18, 0, 0x14000
	v_add_u32_e32 v106, s0, v1
	v_add_u32_e32 v154, s18, v1
	ds_read_b128 v[70:73], v106
	ds_read_b128 v[82:85], v106 offset:1024
	ds_read_b128 v[94:97], v106 offset:2048
	ds_read_b128 v[106:109], v106 offset:3072
	ds_read_b128 v[118:121], v154
	ds_read_b128 v[130:133], v154 offset:1024
	ds_read_b128 v[142:145], v154 offset:2048
	ds_read_b128 v[154:157], v154 offset:3072
	v_lshl_add_u64 v[218:219], s[8:9], 0, v[206:207]
	s_add_i32 m0, s29, 0xc000
	ds_read_b128 v[158:161], v237
	ds_read_b128 v[170:173], v237 offset:1024
	ds_read_b128 v[174:177], v237 offset:2048
	ds_read_b128 v[178:181], v237 offset:3072
	ds_read_b128 v[182:185], v237 offset:4096
	ds_read_b128 v[186:189], v237 offset:5120
	ds_read_b128 v[210:213], v237 offset:6144
	ds_read_b128 v[214:217], v237 offset:7168
	global_load_lds_dwordx4 v[218:219], off
	v_lshl_add_u64 v[218:219], s[8:9], 0, v[208:209]
	s_add_i32 m0, s29, 0xe000
	s_nop 0
	global_load_lds_dwordx4 v[218:219], off
	s_waitcnt vmcnt(8)
	s_barrier
	s_setprio 1
	s_waitcnt lgkmcnt(0)
	v_mfma_f32_16x16x32_bf16 v[166:169], v[70:73], v[158:161], v[166:169]
	v_mfma_f32_16x16x32_bf16 v[162:165], v[94:97], v[158:161], v[162:165]
	v_mfma_f32_16x16x32_bf16 v[138:141], v[70:73], v[174:177], v[138:141]
	v_mfma_f32_16x16x32_bf16 v[134:137], v[94:97], v[174:177], v[134:137]
	v_mfma_f32_16x16x32_bf16 v[114:117], v[70:73], v[182:185], v[114:117]
	v_mfma_f32_16x16x32_bf16 v[110:113], v[94:97], v[182:185], v[110:113]
	v_mfma_f32_16x16x32_bf16 v[90:93], v[70:73], v[210:213], v[90:93]
	v_mfma_f32_16x16x32_bf16 v[86:89], v[94:97], v[210:213], v[86:89]
	v_mfma_f32_16x16x32_bf16 v[166:169], v[82:85], v[170:173], v[166:169]
	v_mfma_f32_16x16x32_bf16 v[162:165], v[106:109], v[170:173], v[162:165]
	v_mfma_f32_16x16x32_bf16 v[138:141], v[82:85], v[178:181], v[138:141]
	v_mfma_f32_16x16x32_bf16 v[134:137], v[106:109], v[178:181], v[134:137]
	v_mfma_f32_16x16x32_bf16 v[114:117], v[82:85], v[186:189], v[114:117]
	v_mfma_f32_16x16x32_bf16 v[110:113], v[106:109], v[186:189], v[110:113]
	v_mfma_f32_16x16x32_bf16 v[90:93], v[82:85], v[214:217], v[90:93]
	v_mfma_f32_16x16x32_bf16 v[86:89], v[106:109], v[214:217], v[86:89]
	s_setprio 0
	s_setprio 1
	v_mfma_f32_16x16x32_bf16 v[150:153], v[118:121], v[158:161], v[150:153]
	v_mfma_f32_16x16x32_bf16 v[146:149], v[142:145], v[158:161], v[146:149]
	v_mfma_f32_16x16x32_bf16 v[126:129], v[118:121], v[174:177], v[126:129]
	v_mfma_f32_16x16x32_bf16 v[122:125], v[142:145], v[174:177], v[122:125]
	v_mfma_f32_16x16x32_bf16 v[102:105], v[118:121], v[182:185], v[102:105]
	v_mfma_f32_16x16x32_bf16 v[98:101], v[142:145], v[182:185], v[98:101]
	v_mfma_f32_16x16x32_bf16 v[78:81], v[118:121], v[210:213], v[78:81]
	v_mfma_f32_16x16x32_bf16 v[74:77], v[142:145], v[210:213], v[74:77]
	v_mfma_f32_16x16x32_bf16 v[150:153], v[130:133], v[170:173], v[150:153]
	v_mfma_f32_16x16x32_bf16 v[146:149], v[154:157], v[170:173], v[146:149]
	v_mfma_f32_16x16x32_bf16 v[126:129], v[130:133], v[178:181], v[126:129]
	v_mfma_f32_16x16x32_bf16 v[122:125], v[154:157], v[178:181], v[122:125]
	v_mfma_f32_16x16x32_bf16 v[102:105], v[130:133], v[186:189], v[102:105]
	v_mfma_f32_16x16x32_bf16 v[98:101], v[154:157], v[186:189], v[98:101]
	v_mfma_f32_16x16x32_bf16 v[78:81], v[130:133], v[214:217], v[78:81]
	v_mfma_f32_16x16x32_bf16 v[74:77], v[154:157], v[214:217], v[74:77]
	s_setprio 0
	s_barrier
	s_add_i32 s0, s0, s28
	v_lshl_add_u64 v[218:219], s[70:71], 0, v[192:193]
	s_mov_b32 m0, s0
	ds_read_b128 v[158:161], v237 offset:16384
	ds_read_b128 v[170:173], v237 offset:17408
	ds_read_b128 v[174:177], v237 offset:18432
	ds_read_b128 v[178:181], v237 offset:19456
	ds_read_b128 v[182:185], v237 offset:20480
	ds_read_b128 v[186:189], v237 offset:21504
	ds_read_b128 v[210:213], v237 offset:22528
	ds_read_b128 v[214:217], v237 offset:23552
	global_load_lds_dwordx4 v[218:219], off
	s_add_i32 m0, s0, 0x2000
	s_add_u32 s0, s70, 0x160000
	v_lshl_add_u64 v[220:221], s[70:71], 0, v[190:191]
	s_addc_u32 s1, s71, 0
	s_add_i32 s8, s18, s28
	global_load_lds_dwordx4 v[220:221], off
	v_lshl_add_u64 v[222:223], s[0:1], 0, v[192:193]
	s_mov_b32 m0, s8
	v_lshl_add_u64 v[224:225], s[76:77], 0, v[190:191]
	global_load_lds_dwordx4 v[222:223], off
	v_lshl_add_u64 v[222:223], s[0:1], 0, v[190:191]
	s_add_i32 m0, s8, 0x2000
	s_nop 0
	global_load_lds_dwordx4 v[222:223], off
	v_lshl_add_u64 v[222:223], s[76:77], 0, v[192:193]
	s_mov_b32 m0, s29
	s_nop 0
	global_load_lds_dwordx4 v[222:223], off
	s_mov_b32 m0, s31
	s_nop 0
	global_load_lds_dwordx4 v[224:225], off
	s_waitcnt vmcnt(8)
	s_barrier
	s_setprio 1
	s_waitcnt lgkmcnt(0)
	v_mfma_f32_16x16x32_bf16 v[62:65], v[70:73], v[158:161], v[62:65]
	v_mfma_f32_16x16x32_bf16 v[58:61], v[94:97], v[158:161], v[58:61]
	v_mfma_f32_16x16x32_bf16 v[46:49], v[70:73], v[174:177], v[46:49]
	v_mfma_f32_16x16x32_bf16 v[42:45], v[94:97], v[174:177], v[42:45]
	v_mfma_f32_16x16x32_bf16 v[30:33], v[70:73], v[182:185], v[30:33]
	v_mfma_f32_16x16x32_bf16 v[26:29], v[94:97], v[182:185], v[26:29]
	v_mfma_f32_16x16x32_bf16 v[14:17], v[70:73], v[210:213], v[14:17]
	v_mfma_f32_16x16x32_bf16 v[10:13], v[94:97], v[210:213], v[10:13]
	v_mfma_f32_16x16x32_bf16 v[62:65], v[82:85], v[170:173], v[62:65]
	v_mfma_f32_16x16x32_bf16 v[58:61], v[106:109], v[170:173], v[58:61]
	v_mfma_f32_16x16x32_bf16 v[46:49], v[82:85], v[178:181], v[46:49]
	v_mfma_f32_16x16x32_bf16 v[42:45], v[106:109], v[178:181], v[42:45]
	v_mfma_f32_16x16x32_bf16 v[30:33], v[82:85], v[186:189], v[30:33]
	v_mfma_f32_16x16x32_bf16 v[26:29], v[106:109], v[186:189], v[26:29]
	v_mfma_f32_16x16x32_bf16 v[14:17], v[82:85], v[214:217], v[14:17]
	v_mfma_f32_16x16x32_bf16 v[10:13], v[106:109], v[214:217], v[10:13]
	s_setprio 0
	s_setprio 1
	v_mfma_f32_16x16x32_bf16 v[54:57], v[118:121], v[158:161], v[54:57]
	v_mfma_f32_16x16x32_bf16 v[50:53], v[142:145], v[158:161], v[50:53]
	v_mfma_f32_16x16x32_bf16 v[38:41], v[118:121], v[174:177], v[38:41]
	v_mfma_f32_16x16x32_bf16 v[34:37], v[142:145], v[174:177], v[34:37]
	v_mfma_f32_16x16x32_bf16 v[22:25], v[118:121], v[182:185], v[22:25]
	v_mfma_f32_16x16x32_bf16 v[18:21], v[142:145], v[182:185], v[18:21]
	v_mfma_f32_16x16x32_bf16 v[6:9], v[118:121], v[210:213], v[6:9]
	v_mfma_f32_16x16x32_bf16 v[2:5], v[142:145], v[210:213], v[2:5]
	v_mfma_f32_16x16x32_bf16 v[54:57], v[130:133], v[170:173], v[54:57]
	v_mfma_f32_16x16x32_bf16 v[50:53], v[154:157], v[170:173], v[50:53]
	v_mfma_f32_16x16x32_bf16 v[38:41], v[130:133], v[178:181], v[38:41]
	v_mfma_f32_16x16x32_bf16 v[34:37], v[154:157], v[178:181], v[34:37]
	v_mfma_f32_16x16x32_bf16 v[22:25], v[130:133], v[186:189], v[22:25]
	v_mfma_f32_16x16x32_bf16 v[18:21], v[154:157], v[186:189], v[18:21]
	v_mfma_f32_16x16x32_bf16 v[6:9], v[130:133], v[214:217], v[6:9]
	v_mfma_f32_16x16x32_bf16 v[2:5], v[154:157], v[214:217], v[2:5]
	s_setprio 0
	s_barrier
	s_add_i32 s8, 0, 0x18000
	s_add_i32 s9, 0, 0x1c000
	v_add_u32_e32 v106, s8, v1
	v_add_u32_e32 v154, s9, v1
	ds_read_b128 v[70:73], v106
	ds_read_b128 v[82:85], v106 offset:1024
	ds_read_b128 v[94:97], v106 offset:2048
	ds_read_b128 v[106:109], v106 offset:3072
	ds_read_b128 v[118:121], v154
	ds_read_b128 v[130:133], v154 offset:1024
	ds_read_b128 v[142:145], v154 offset:2048
	ds_read_b128 v[154:157], v154 offset:3072
	s_add_u32 s0, s76, 0x160000
	s_addc_u32 s1, s77, 0
	s_mov_b32 m0, s33
	v_lshl_add_u64 v[226:227], s[0:1], 0, v[192:193]
	ds_read_b128 v[158:161], v237 offset:32768
	ds_read_b128 v[170:173], v237 offset:33792
	ds_read_b128 v[174:177], v237 offset:34816
	ds_read_b128 v[178:181], v237 offset:35840
	ds_read_b128 v[182:185], v237 offset:36864
	ds_read_b128 v[186:189], v237 offset:37888
	ds_read_b128 v[210:213], v237 offset:38912
	ds_read_b128 v[214:217], v237 offset:39936
	global_load_lds_dwordx4 v[226:227], off
	v_lshl_add_u64 v[226:227], s[0:1], 0, v[190:191]
	s_mov_b32 m0, s43
	s_nop 0
	global_load_lds_dwordx4 v[226:227], off
	s_waitcnt vmcnt(8)
	s_barrier
	s_setprio 1
	s_waitcnt lgkmcnt(0)
	v_mfma_f32_16x16x32_bf16 v[166:169], v[70:73], v[158:161], v[166:169]
	v_mfma_f32_16x16x32_bf16 v[162:165], v[94:97], v[158:161], v[162:165]
	v_mfma_f32_16x16x32_bf16 v[138:141], v[70:73], v[174:177], v[138:141]
	v_mfma_f32_16x16x32_bf16 v[134:137], v[94:97], v[174:177], v[134:137]
	v_mfma_f32_16x16x32_bf16 v[114:117], v[70:73], v[182:185], v[114:117]
	v_mfma_f32_16x16x32_bf16 v[110:113], v[94:97], v[182:185], v[110:113]
	v_mfma_f32_16x16x32_bf16 v[90:93], v[70:73], v[210:213], v[90:93]
	v_mfma_f32_16x16x32_bf16 v[86:89], v[94:97], v[210:213], v[86:89]
	v_mfma_f32_16x16x32_bf16 v[166:169], v[82:85], v[170:173], v[166:169]
	v_mfma_f32_16x16x32_bf16 v[162:165], v[106:109], v[170:173], v[162:165]
	v_mfma_f32_16x16x32_bf16 v[138:141], v[82:85], v[178:181], v[138:141]
	v_mfma_f32_16x16x32_bf16 v[134:137], v[106:109], v[178:181], v[134:137]
	v_mfma_f32_16x16x32_bf16 v[114:117], v[82:85], v[186:189], v[114:117]
	v_mfma_f32_16x16x32_bf16 v[110:113], v[106:109], v[186:189], v[110:113]
	v_mfma_f32_16x16x32_bf16 v[90:93], v[82:85], v[214:217], v[90:93]
	v_mfma_f32_16x16x32_bf16 v[86:89], v[106:109], v[214:217], v[86:89]
	s_setprio 0
	s_setprio 1
	v_mfma_f32_16x16x32_bf16 v[150:153], v[118:121], v[158:161], v[150:153]
	v_mfma_f32_16x16x32_bf16 v[146:149], v[142:145], v[158:161], v[146:149]
	v_mfma_f32_16x16x32_bf16 v[126:129], v[118:121], v[174:177], v[126:129]
	v_mfma_f32_16x16x32_bf16 v[122:125], v[142:145], v[174:177], v[122:125]
	v_mfma_f32_16x16x32_bf16 v[102:105], v[118:121], v[182:185], v[102:105]
	v_mfma_f32_16x16x32_bf16 v[98:101], v[142:145], v[182:185], v[98:101]
	v_mfma_f32_16x16x32_bf16 v[78:81], v[118:121], v[210:213], v[78:81]
	v_mfma_f32_16x16x32_bf16 v[74:77], v[142:145], v[210:213], v[74:77]
	v_mfma_f32_16x16x32_bf16 v[150:153], v[130:133], v[170:173], v[150:153]
	v_mfma_f32_16x16x32_bf16 v[146:149], v[154:157], v[170:173], v[146:149]
	v_mfma_f32_16x16x32_bf16 v[126:129], v[130:133], v[178:181], v[126:129]
	v_mfma_f32_16x16x32_bf16 v[122:125], v[154:157], v[178:181], v[122:125]
	v_mfma_f32_16x16x32_bf16 v[102:105], v[130:133], v[186:189], v[102:105]
	v_mfma_f32_16x16x32_bf16 v[98:101], v[154:157], v[186:189], v[98:101]
	v_mfma_f32_16x16x32_bf16 v[78:81], v[130:133], v[214:217], v[78:81]
	v_mfma_f32_16x16x32_bf16 v[74:77], v[154:157], v[214:217], v[74:77]
	s_setprio 0
	s_barrier
	s_add_i32 s0, s8, s28
	v_lshl_add_u64 v[218:219], v[218:219], 0, s[82:83]
	s_mov_b32 m0, s0
	ds_read_b128 v[158:161], v237 offset:49152
	ds_read_b128 v[170:173], v237 offset:50176
	ds_read_b128 v[174:177], v237 offset:51200
	ds_read_b128 v[178:181], v237 offset:52224
	ds_read_b128 v[182:185], v237 offset:53248
	ds_read_b128 v[186:189], v237 offset:54272
	ds_read_b128 v[210:213], v237 offset:55296
	ds_read_b128 v[214:217], v237 offset:56320
	global_load_lds_dwordx4 v[218:219], off
	s_add_i32 m0, s0, 0x2000
	s_add_u32 s0, s70, 0x160080
	v_lshl_add_u64 v[218:219], v[220:221], 0, s[82:83]
	s_addc_u32 s1, s71, 0
	s_add_i32 s8, s9, s28
	global_load_lds_dwordx4 v[218:219], off
	v_lshl_add_u64 v[218:219], s[0:1], 0, v[192:193]
	s_mov_b32 m0, s8
	s_nop 0
	global_load_lds_dwordx4 v[218:219], off
	v_lshl_add_u64 v[218:219], s[0:1], 0, v[190:191]
	s_add_i32 m0, s8, 0x2000
	s_nop 0
	global_load_lds_dwordx4 v[218:219], off
	v_lshl_add_u64 v[218:219], v[222:223], 0, s[82:83]
	s_mov_b32 m0, s68
	s_nop 0
	global_load_lds_dwordx4 v[218:219], off
	v_lshl_add_u64 v[218:219], v[224:225], 0, s[82:83]
	s_mov_b32 m0, s79
	s_nop 0
	global_load_lds_dwordx4 v[218:219], off
	s_waitcnt vmcnt(8)
	s_barrier
	s_setprio 1
	s_waitcnt lgkmcnt(0)
	v_mfma_f32_16x16x32_bf16 v[62:65], v[70:73], v[158:161], v[62:65]
	v_mfma_f32_16x16x32_bf16 v[58:61], v[94:97], v[158:161], v[58:61]
	v_mfma_f32_16x16x32_bf16 v[46:49], v[70:73], v[174:177], v[46:49]
	v_mfma_f32_16x16x32_bf16 v[42:45], v[94:97], v[174:177], v[42:45]
	v_mfma_f32_16x16x32_bf16 v[30:33], v[70:73], v[182:185], v[30:33]
	v_mfma_f32_16x16x32_bf16 v[26:29], v[94:97], v[182:185], v[26:29]
	v_mfma_f32_16x16x32_bf16 v[14:17], v[70:73], v[210:213], v[14:17]
	v_mfma_f32_16x16x32_bf16 v[10:13], v[94:97], v[210:213], v[10:13]
	v_mfma_f32_16x16x32_bf16 v[62:65], v[82:85], v[170:173], v[62:65]
	v_mfma_f32_16x16x32_bf16 v[58:61], v[106:109], v[170:173], v[58:61]
	v_mfma_f32_16x16x32_bf16 v[46:49], v[82:85], v[178:181], v[46:49]
	v_mfma_f32_16x16x32_bf16 v[42:45], v[106:109], v[178:181], v[42:45]
	v_mfma_f32_16x16x32_bf16 v[30:33], v[82:85], v[186:189], v[30:33]
	v_mfma_f32_16x16x32_bf16 v[26:29], v[106:109], v[186:189], v[26:29]
	v_mfma_f32_16x16x32_bf16 v[14:17], v[82:85], v[214:217], v[14:17]
	v_mfma_f32_16x16x32_bf16 v[10:13], v[106:109], v[214:217], v[10:13]
	s_setprio 0
	s_setprio 1
	v_mfma_f32_16x16x32_bf16 v[54:57], v[118:121], v[158:161], v[54:57]
	v_mfma_f32_16x16x32_bf16 v[50:53], v[142:145], v[158:161], v[50:53]
	v_mfma_f32_16x16x32_bf16 v[38:41], v[118:121], v[174:177], v[38:41]
	v_mfma_f32_16x16x32_bf16 v[34:37], v[142:145], v[174:177], v[34:37]
	v_mfma_f32_16x16x32_bf16 v[22:25], v[118:121], v[182:185], v[22:25]
	v_mfma_f32_16x16x32_bf16 v[18:21], v[142:145], v[182:185], v[18:21]
	v_mfma_f32_16x16x32_bf16 v[6:9], v[118:121], v[210:213], v[6:9]
	v_mfma_f32_16x16x32_bf16 v[2:5], v[142:145], v[210:213], v[2:5]
	v_mfma_f32_16x16x32_bf16 v[54:57], v[130:133], v[170:173], v[54:57]
	v_mfma_f32_16x16x32_bf16 v[50:53], v[154:157], v[170:173], v[50:53]
	v_mfma_f32_16x16x32_bf16 v[38:41], v[130:133], v[178:181], v[38:41]
	v_mfma_f32_16x16x32_bf16 v[34:37], v[154:157], v[178:181], v[34:37]
	v_mfma_f32_16x16x32_bf16 v[22:25], v[130:133], v[186:189], v[22:25]
	v_mfma_f32_16x16x32_bf16 v[18:21], v[154:157], v[186:189], v[18:21]
	v_mfma_f32_16x16x32_bf16 v[6:9], v[130:133], v[214:217], v[6:9]
	v_mfma_f32_16x16x32_bf16 v[2:5], v[154:157], v[214:217], v[2:5]
	s_setprio 0
	s_barrier
	s_add_i32 s41, s41, 2
	s_add_u32 s7, s7, 0x100
	s_addc_u32 s23, s23, 0
	s_cmpk_gt_u32 s41, 0x55
	s_mov_b64 s[8:9], s[64:65]
	s_cbranch_scc1 .LBB0_648
